# E4 + EpiRes2 (P4/P8) epilogue vmcnt waits recomputed to count the always-executed stats atomics (waits no longer cover the two newest out-stores)
# speedup vs baseline: 1.0096x; 1.0068x over previous
; __device__ __forceinline__ unsigned cvt_pk_bf16(float lo, float hi) { unsigned r; asm volatile("v_cvt_pk_bf16_f32 %0, %1, %2" : "=v"(r) : "v"(lo), "v"(hi)); return r; }
; __device__ __forceinline__ void stats_mr(const f32x2 s, float& mu, float& r) { mu = s.x * (1.0f / 1024.0f); const float var = s.y * (1.0f / 1024.0f) - mu * mu; r = __builtin_amdgcn_rsqf(var + 1e-5f); }
;     __device__ __forceinline__ void operator()(const f32x4 (&acc)[2][2][4][2], const Unit& u, int wr, int wc, int fr, int fq) const {
;     ...
;         for (int g = 0; g < 8; ++g) { const int ai = g >> 2, m = g & 3; const int rr = ai * HALF + m * 16, rn = ((g + 1) >> 2) * HALF + ((g + 1) & 3) * 16;
;             f32x2 sv_n = sv_c; if (g + 1 < 8) sv_n = *(const f32x2*)(sp + (size_t)rn * 8 + ls);
;             float mu, r; stats_mr(sv_c, mu, r); float s1 = 0.f, s2 = 0.f;
; #pragma unroll
;             for (int bj = 0; bj < 2; ++bj) { const size_t ro = (size_t)rr * ldc + bj * HALF;
;                 f32x4 q0 = p0, q1 = p1;
;                 if (bj == 0) { q0 = *(const f32x4*)(bp + (ro + HALF) * 4 + l4); q1 = *(const f32x4*)(bp + (ro + HALF) * 4 + l4 + 16); }
;                 else if (g + 1 < 8) { q0 = *(const f32x4*)(bp + (size_t)rn * ldc * 4 + l4); q1 = *(const f32x4*)(bp + (size_t)rn * ldc * 4 + l4 + 16); }
;                 const f32x4 z0 = gv[bj][0] * ((p0 - mu) * r) + acc[ai][bj][m][0] + cv[bj][0], z1 = gv[bj][1] * ((p1 - mu) * r) + acc[ai][bj][m][1] + cv[bj][1];
;                 *(f32x4*)(op + ro * 4 + l4) = z0; *(f32x4*)(op + ro * 4 + l4 + 16) = z1;
;                 s1 += ((z0[0] + z0[1]) + (z0[2] + z0[3])) + ((z1[0] + z1[1]) + (z1[2] + z1[3]));
;                 s2 += ((z0[0] * z0[0] + z0[1] * z0[1]) + (z0[2] * z0[2] + z0[3] * z0[3])) + ((z1[0] * z1[0] + z1[1] * z1[1]) + (z1[2] * z1[2] + z1[3] * z1[3]));
;                 if (zb) { u32x4 w; w.x = cvt_pk_bf16(z0[0], z0[1]); w.y = cvt_pk_bf16(z0[2], z0[3]); w.z = cvt_pk_bf16(z1[0], z1[1]); w.w = cvt_pk_bf16(z1[2], z1[3]); *(u32x4*)(zp + ro * 2 + l2) = w; }
;                 p0 = q0; p1 = q1; }
;             s1 += __shfl_xor(s1, 16); s2 += __shfl_xor(s2, 16); s1 += __shfl_xor(s1, 32); s2 += __shfl_xor(s2, 32);
;             if (fq == 0) { atomicAdd(osp + 2 * (rr + fr), s1); atomicAdd(osp + 2 * (rr + fr) + 1, s2); }
;             sv_c = sv_n; }
.LBB0_732:
	s_or_b64 exec, exec, s[24:25]
	v_pk_mul_f32 v[134:135], v[206:207], s[54:55] op_sel_hi:[1,0]
	s_mov_b64 s[24:25], 0x10200
	v_fma_f32 v114, -v134, v134, v135
	v_add_f32_e32 v114, 0x3727c5ac, v114
	v_rsq_f32_e32 v132, v114
	v_lshl_add_u64 v[114:115], v[202:203], 0, s[24:25]
	global_load_dwordx2 v[130:131], v[204:205], off offset:256
	global_load_dwordx4 v[118:121], v[212:213], off offset:512
	s_waitcnt lgkmcnt(0)
	global_load_dwordx4 v[114:117], v[114:115], off offset:16
	s_waitcnt vmcnt(9)
	v_sub_f32_e32 v127, v127, v134
	v_sub_f32_e32 v126, v126, v134
	v_sub_f32_e32 v129, v129, v134
	v_sub_f32_e32 v128, v128, v134
	v_pk_mul_f32 v[128:129], v[132:133], v[128:129] op_sel_hi:[0,1]
	v_pk_mul_f32 v[126:127], v[132:133], v[126:127] op_sel_hi:[0,1]
	s_waitcnt vmcnt(8)
	v_sub_f32_e32 v123, v123, v134
	v_sub_f32_e32 v122, v122, v134
	v_sub_f32_e32 v125, v125, v134
	v_sub_f32_e32 v124, v124, v134
	v_pk_fma_f32 v[110:111], v[170:171], v[126:127], v[110:111]
	v_pk_fma_f32 v[112:113], v[162:163], v[128:129], v[112:113]
	v_pk_mul_f32 v[124:125], v[132:133], v[124:125] op_sel_hi:[0,1]
	v_pk_mul_f32 v[122:123], v[132:133], v[122:123] op_sel_hi:[0,1]
	v_pk_add_f32 v[112:113], v[186:187], v[112:113]
	v_pk_add_f32 v[110:111], v[188:189], v[110:111]
	v_pk_fma_f32 v[106:107], v[196:197], v[122:123], v[106:107]
	v_pk_fma_f32 v[108:109], v[194:195], v[124:125], v[108:109]
	v_pk_add_f32 v[106:107], v[192:193], v[106:107]
	v_pk_add_f32 v[108:109], v[190:191], v[108:109]
	v_add_f32_e32 v122, v110, v111
	v_add_f32_e32 v123, v112, v113
	v_add_f32_e32 v122, v122, v123
	v_add_f32_e32 v123, v106, v107
	v_add_f32_e32 v126, v108, v109
	v_add_f32_e32 v123, v123, v126
	v_add_f32_e32 v122, v122, v123
	v_add_f32_e32 v128, 0, v122
	v_mul_f32_e32 v122, v111, v111
	v_mul_f32_e32 v123, v113, v113
	v_fmac_f32_e32 v122, v110, v110
	v_fmac_f32_e32 v123, v112, v112
	v_add_co_u32_e32 v124, vcc, s4, v200
	v_add_f32_e32 v122, v122, v123
	v_mul_f32_e32 v123, v107, v107
	v_mul_f32_e32 v126, v109, v109
	v_addc_co_u32_e32 v125, vcc, 0, v201, vcc
	v_fmac_f32_e32 v123, v106, v106
	v_fmac_f32_e32 v126, v108, v108
	s_mov_b32 s1, 0x8000
	v_add_f32_e32 v123, v123, v126
	v_add_co_u32_e32 v126, vcc, s1, v198
	s_mov_b32 s1, 0x20000
	s_nop 0
	v_addc_co_u32_e32 v127, vcc, 0, v199, vcc
	v_add_f32_e32 v129, v122, v123
	s_mov_b64 s[24:25], 0x20000
	v_add_co_u32_e32 v122, vcc, s1, v202
	global_store_dwordx4 v[124:125], v[110:113], off nt
	global_store_dwordx4 v[124:125], v[106:109], off offset:16 nt
	v_addc_co_u32_e32 v123, vcc, 0, v203, vcc
	v_cvt_pk_bf16_f32 v110, v110, v111
	v_cvt_pk_bf16_f32 v111, v112, v113
	v_cvt_pk_bf16_f32 v112, v106, v107
	v_cvt_pk_bf16_f32 v113, v108, v109
	global_store_dwordx4 v[126:127], v[110:113], off
	v_lshl_add_u64 v[106:107], v[202:203], 0, s[24:25]
	global_load_dwordx4 v[110:113], v[122:123], off
	s_nop 0
	global_load_dwordx4 v[106:109], v[106:107], off offset:16
	s_waitcnt vmcnt(6)
	v_sub_f32_e32 v119, v119, v134
	v_sub_f32_e32 v118, v118, v134
	v_sub_f32_e32 v121, v121, v134
	v_sub_f32_e32 v120, v120, v134
	v_pk_mul_f32 v[120:121], v[132:133], v[120:121] op_sel_hi:[0,1]
	v_pk_mul_f32 v[118:119], v[132:133], v[118:119] op_sel_hi:[0,1]
	s_waitcnt vmcnt(5)
	v_sub_f32_e32 v115, v115, v134
	v_sub_f32_e32 v114, v114, v134
	v_sub_f32_e32 v117, v117, v134
	v_sub_f32_e32 v116, v116, v134
	v_pk_fma_f32 v[102:103], v[164:165], v[118:119], v[102:103]
	v_pk_fma_f32 v[104:105], v[160:161], v[120:121], v[104:105]
	v_pk_mul_f32 v[116:117], v[132:133], v[116:117] op_sel_hi:[0,1]
	v_pk_mul_f32 v[114:115], v[132:133], v[114:115] op_sel_hi:[0,1]
	v_pk_add_f32 v[104:105], v[174:175], v[104:105]
	v_pk_add_f32 v[102:103], v[176:177], v[102:103]
	v_pk_fma_f32 v[98:99], v[178:179], v[114:115], v[98:99]
	v_pk_fma_f32 v[100:101], v[172:173], v[116:117], v[100:101]
	v_pk_add_f32 v[98:99], v[168:169], v[98:99]
	v_pk_add_f32 v[100:101], v[166:167], v[100:101]
	v_add_f32_e32 v114, v102, v103
	v_add_f32_e32 v115, v104, v105
	v_add_f32_e32 v114, v114, v115
	v_add_f32_e32 v115, v98, v99
	v_add_f32_e32 v116, v100, v101
	v_add_f32_e32 v115, v115, v116
	v_add_f32_e32 v114, v114, v115
	v_mul_f32_e32 v115, v103, v103
	v_mul_f32_e32 v116, v105, v105
	v_fmac_f32_e32 v115, v102, v102
	v_fmac_f32_e32 v116, v104, v104
	v_add_f32_e32 v115, v115, v116
	v_mul_f32_e32 v116, v99, v99
	v_mul_f32_e32 v117, v101, v101
	v_fmac_f32_e32 v116, v98, v98
	v_fmac_f32_e32 v117, v100, v100
	v_add_f32_e32 v116, v116, v117
	v_add_f32_e32 v115, v115, v116
	v_add_f32_e32 v114, v128, v114
	v_add_f32_e32 v115, v129, v115
	global_store_dwordx4 v[124:125], v[102:105], off offset:512 nt
	global_store_dwordx4 v[124:125], v[98:101], off offset:528 nt
	s_nop 0
	v_cvt_pk_bf16_f32 v102, v102, v103
	v_cvt_pk_bf16_f32 v103, v104, v105
	v_cvt_pk_bf16_f32 v104, v98, v99
	ds_bpermute_b32 v98, v133, v114
	ds_bpermute_b32 v99, v133, v115
	v_cvt_pk_bf16_f32 v105, v100, v101
	global_store_dwordx4 v[126:127], v[102:105], off offset:256
	s_waitcnt lgkmcnt(1)
	v_add_f32_e32 v98, v114, v98
	s_waitcnt lgkmcnt(0)
	v_add_f32_e32 v99, v115, v99
	ds_bpermute_b32 v100, v136, v98
	ds_bpermute_b32 v101, v136, v99
	s_and_saveexec_b64 s[24:25], s[40:41]
	s_cbranch_execz .LBB0_734
	s_waitcnt lgkmcnt(1)
	v_add_f32_e32 v98, v98, v100
	s_waitcnt lgkmcnt(0)
	v_add_f32_e32 v99, v99, v101
	global_atomic_add_f32 v137, v98, s[82:83] offset:128
	global_atomic_add_f32 v137, v99, s[82:83] offset:132
; __device__ __forceinline__ unsigned cvt_pk_bf16(float lo, float hi) { unsigned r; asm volatile("v_cvt_pk_bf16_f32 %0, %1, %2" : "=v"(r) : "v"(lo), "v"(hi)); return r; }
; __device__ __forceinline__ void stats_mr(const f32x2 s, float& mu, float& r) { mu = s.x * (1.0f / 1024.0f); const float var = s.y * (1.0f / 1024.0f) - mu * mu; r = __builtin_amdgcn_rsqf(var + 1e-5f); }
;     __device__ __forceinline__ void operator()(const f32x4 (&acc)[2][2][4][2], const Unit& u, int wr, int wc, int fr, int fq) const {
;     ...
;         for (int g = 0; g < 8; ++g) { const int ai = g >> 2, m = g & 3; const int rr = ai * HALF + m * 16, rn = ((g + 1) >> 2) * HALF + ((g + 1) & 3) * 16;
;             f32x2 sv_n = sv_c; if (g + 1 < 8) sv_n = *(const f32x2*)(sp + (size_t)rn * 8 + ls);
;             float mu, r; stats_mr(sv_c, mu, r); float s1 = 0.f, s2 = 0.f;
; #pragma unroll
;             for (int bj = 0; bj < 2; ++bj) { const size_t ro = (size_t)rr * ldc + bj * HALF;
;                 f32x4 q0 = p0, q1 = p1;
;                 if (bj == 0) { q0 = *(const f32x4*)(bp + (ro + HALF) * 4 + l4); q1 = *(const f32x4*)(bp + (ro + HALF) * 4 + l4 + 16); }
;                 else if (g + 1 < 8) { q0 = *(const f32x4*)(bp + (size_t)rn * ldc * 4 + l4); q1 = *(const f32x4*)(bp + (size_t)rn * ldc * 4 + l4 + 16); }
;                 const f32x4 z0 = gv[bj][0] * ((p0 - mu) * r) + acc[ai][bj][m][0] + cv[bj][0], z1 = gv[bj][1] * ((p1 - mu) * r) + acc[ai][bj][m][1] + cv[bj][1];
;                 *(f32x4*)(op + ro * 4 + l4) = z0; *(f32x4*)(op + ro * 4 + l4 + 16) = z1;
;                 s1 += ((z0[0] + z0[1]) + (z0[2] + z0[3])) + ((z1[0] + z1[1]) + (z1[2] + z1[3]));
;                 s2 += ((z0[0] * z0[0] + z0[1] * z0[1]) + (z0[2] * z0[2] + z0[3] * z0[3])) + ((z1[0] * z1[0] + z1[1] * z1[1]) + (z1[2] * z1[2] + z1[3] * z1[3]));
;                 if (zb) { u32x4 w; w.x = cvt_pk_bf16(z0[0], z0[1]); w.y = cvt_pk_bf16(z0[2], z0[3]); w.z = cvt_pk_bf16(z1[0], z1[1]); w.w = cvt_pk_bf16(z1[2], z1[3]); *(u32x4*)(zp + ro * 2 + l2) = w; }
;                 p0 = q0; p1 = q1; }
;             s1 += __shfl_xor(s1, 16); s2 += __shfl_xor(s2, 16); s1 += __shfl_xor(s1, 32); s2 += __shfl_xor(s2, 32);
;             if (fq == 0) { atomicAdd(osp + 2 * (rr + fr), s1); atomicAdd(osp + 2 * (rr + fr) + 1, s2); }
;             sv_c = sv_n; }
.LBB0_734:
	s_or_b64 exec, exec, s[24:25]
	v_pk_mul_f32 v[118:119], v[130:131], s[54:55] op_sel_hi:[1,0]
	s_mov_b64 s[24:25], 0x20200
	v_fma_f32 v98, -v118, v118, v119
	v_add_f32_e32 v98, 0x3727c5ac, v98
	v_rsq_f32_e32 v116, v98
	v_lshl_add_u64 v[98:99], v[202:203], 0, s[24:25]
	global_load_dwordx2 v[114:115], v[204:205], off offset:384
	global_load_dwordx4 v[102:105], v[122:123], off offset:512
	s_waitcnt lgkmcnt(0)
	global_load_dwordx4 v[98:101], v[98:99], off offset:16
	s_waitcnt vmcnt(9)
	v_sub_f32_e32 v111, v111, v118
	v_sub_f32_e32 v110, v110, v118
	v_sub_f32_e32 v113, v113, v118
	v_sub_f32_e32 v112, v112, v118
	v_pk_mul_f32 v[112:113], v[116:117], v[112:113] op_sel_hi:[0,1]
	v_pk_mul_f32 v[110:111], v[116:117], v[110:111] op_sel_hi:[0,1]
	s_waitcnt vmcnt(8)
	v_sub_f32_e32 v107, v107, v118
	v_sub_f32_e32 v106, v106, v118
	v_sub_f32_e32 v109, v109, v118
	v_sub_f32_e32 v108, v108, v118
	v_pk_fma_f32 v[94:95], v[170:171], v[110:111], v[94:95]
	v_pk_fma_f32 v[96:97], v[162:163], v[112:113], v[96:97]
	v_pk_mul_f32 v[108:109], v[116:117], v[108:109] op_sel_hi:[0,1]
	v_pk_mul_f32 v[106:107], v[116:117], v[106:107] op_sel_hi:[0,1]
	v_pk_add_f32 v[96:97], v[186:187], v[96:97]
	v_pk_add_f32 v[94:95], v[188:189], v[94:95]
	v_pk_fma_f32 v[90:91], v[196:197], v[106:107], v[90:91]
	v_pk_fma_f32 v[92:93], v[194:195], v[108:109], v[92:93]
	v_pk_add_f32 v[90:91], v[192:193], v[90:91]
	v_pk_add_f32 v[92:93], v[190:191], v[92:93]
	v_add_f32_e32 v106, v94, v95
	v_add_f32_e32 v107, v96, v97
	v_add_f32_e32 v106, v106, v107
	v_add_f32_e32 v107, v90, v91
	v_add_f32_e32 v110, v92, v93
	v_add_f32_e32 v107, v107, v110
	v_add_f32_e32 v106, v106, v107
	v_add_f32_e32 v112, 0, v106
	v_mul_f32_e32 v106, v95, v95
	v_mul_f32_e32 v107, v97, v97
	v_fmac_f32_e32 v106, v94, v94
	v_fmac_f32_e32 v107, v96, v96
	v_add_co_u32_e32 v108, vcc, s1, v200
	v_add_f32_e32 v106, v106, v107
	v_mul_f32_e32 v107, v91, v91
	v_mul_f32_e32 v110, v93, v93
	v_addc_co_u32_e32 v109, vcc, 0, v201, vcc
	v_fmac_f32_e32 v107, v90, v90
	v_fmac_f32_e32 v110, v92, v92
	v_add_f32_e32 v107, v107, v110
	v_add_co_u32_e32 v110, vcc, s4, v198
	s_mov_b32 s1, 0x30000
	s_nop 0
	v_addc_co_u32_e32 v111, vcc, 0, v199, vcc
	v_add_f32_e32 v113, v106, v107
	s_mov_b64 s[24:25], 0x30000
	v_add_co_u32_e32 v106, vcc, s1, v202
	global_store_dwordx4 v[108:109], v[94:97], off nt
	global_store_dwordx4 v[108:109], v[90:93], off offset:16 nt
	v_addc_co_u32_e32 v107, vcc, 0, v203, vcc
	v_cvt_pk_bf16_f32 v94, v94, v95
	v_cvt_pk_bf16_f32 v95, v96, v97
	v_cvt_pk_bf16_f32 v96, v90, v91
	v_cvt_pk_bf16_f32 v97, v92, v93
	global_store_dwordx4 v[110:111], v[94:97], off
	v_lshl_add_u64 v[90:91], v[202:203], 0, s[24:25]
	global_load_dwordx4 v[94:97], v[106:107], off
	s_nop 0
	global_load_dwordx4 v[90:93], v[90:91], off offset:16
	s_waitcnt vmcnt(6)
	v_sub_f32_e32 v103, v103, v118
	v_sub_f32_e32 v102, v102, v118
	v_sub_f32_e32 v105, v105, v118
	v_sub_f32_e32 v104, v104, v118
	v_pk_mul_f32 v[104:105], v[116:117], v[104:105] op_sel_hi:[0,1]
	v_pk_mul_f32 v[102:103], v[116:117], v[102:103] op_sel_hi:[0,1]
	s_waitcnt vmcnt(5)
	v_sub_f32_e32 v99, v99, v118
	v_sub_f32_e32 v98, v98, v118
	v_sub_f32_e32 v101, v101, v118
	v_sub_f32_e32 v100, v100, v118
	v_pk_fma_f32 v[86:87], v[164:165], v[102:103], v[86:87]
	v_pk_fma_f32 v[88:89], v[160:161], v[104:105], v[88:89]
	v_pk_mul_f32 v[100:101], v[116:117], v[100:101] op_sel_hi:[0,1]
	v_pk_mul_f32 v[98:99], v[116:117], v[98:99] op_sel_hi:[0,1]
	v_pk_add_f32 v[88:89], v[174:175], v[88:89]
	v_pk_add_f32 v[86:87], v[176:177], v[86:87]
	v_pk_fma_f32 v[82:83], v[178:179], v[98:99], v[82:83]
	v_pk_fma_f32 v[84:85], v[172:173], v[100:101], v[84:85]
	v_pk_add_f32 v[82:83], v[168:169], v[82:83]
	v_pk_add_f32 v[84:85], v[166:167], v[84:85]
	v_add_f32_e32 v98, v86, v87
	v_add_f32_e32 v99, v88, v89
	v_add_f32_e32 v98, v98, v99
	v_add_f32_e32 v99, v82, v83
	v_add_f32_e32 v100, v84, v85
	v_add_f32_e32 v99, v99, v100
	v_add_f32_e32 v98, v98, v99
	v_mul_f32_e32 v99, v87, v87
	v_mul_f32_e32 v100, v89, v89
	v_fmac_f32_e32 v99, v86, v86
	v_fmac_f32_e32 v100, v88, v88
	v_add_f32_e32 v99, v99, v100
	v_mul_f32_e32 v100, v83, v83
	v_mul_f32_e32 v101, v85, v85
	v_fmac_f32_e32 v100, v82, v82
	v_fmac_f32_e32 v101, v84, v84
	v_add_f32_e32 v100, v100, v101
	v_add_f32_e32 v99, v99, v100
	v_add_f32_e32 v98, v112, v98
	v_add_f32_e32 v99, v113, v99
	global_store_dwordx4 v[108:109], v[86:89], off offset:512 nt
	global_store_dwordx4 v[108:109], v[82:85], off offset:528 nt
	s_nop 0
	v_cvt_pk_bf16_f32 v86, v86, v87
	v_cvt_pk_bf16_f32 v87, v88, v89
	v_cvt_pk_bf16_f32 v88, v82, v83
	ds_bpermute_b32 v82, v133, v98
	ds_bpermute_b32 v83, v133, v99
	v_cvt_pk_bf16_f32 v89, v84, v85
	global_store_dwordx4 v[110:111], v[86:89], off offset:256
	s_waitcnt lgkmcnt(1)
	v_add_f32_e32 v82, v98, v82
	s_waitcnt lgkmcnt(0)
	v_add_f32_e32 v83, v99, v83
	ds_bpermute_b32 v84, v136, v82
	ds_bpermute_b32 v85, v136, v83
	s_and_saveexec_b64 s[24:25], s[40:41]
	s_cbranch_execz .LBB0_736
	s_waitcnt lgkmcnt(1)
	v_add_f32_e32 v82, v82, v84
	s_waitcnt lgkmcnt(0)
	v_add_f32_e32 v83, v83, v85
	global_atomic_add_f32 v137, v82, s[82:83] offset:256
	global_atomic_add_f32 v137, v83, s[82:83] offset:260
; __device__ __forceinline__ unsigned cvt_pk_bf16(float lo, float hi) { unsigned r; asm volatile("v_cvt_pk_bf16_f32 %0, %1, %2" : "=v"(r) : "v"(lo), "v"(hi)); return r; }
; __device__ __forceinline__ void stats_mr(const f32x2 s, float& mu, float& r) { mu = s.x * (1.0f / 1024.0f); const float var = s.y * (1.0f / 1024.0f) - mu * mu; r = __builtin_amdgcn_rsqf(var + 1e-5f); }
;     __device__ __forceinline__ void operator()(const f32x4 (&acc)[2][2][4][2], const Unit& u, int wr, int wc, int fr, int fq) const {
;     ...
;         for (int g = 0; g < 8; ++g) { const int ai = g >> 2, m = g & 3; const int rr = ai * HALF + m * 16, rn = ((g + 1) >> 2) * HALF + ((g + 1) & 3) * 16;
;             f32x2 sv_n = sv_c; if (g + 1 < 8) sv_n = *(const f32x2*)(sp + (size_t)rn * 8 + ls);
;             float mu, r; stats_mr(sv_c, mu, r); float s1 = 0.f, s2 = 0.f;
; #pragma unroll
;             for (int bj = 0; bj < 2; ++bj) { const size_t ro = (size_t)rr * ldc + bj * HALF;
;                 f32x4 q0 = p0, q1 = p1;
;                 if (bj == 0) { q0 = *(const f32x4*)(bp + (ro + HALF) * 4 + l4); q1 = *(const f32x4*)(bp + (ro + HALF) * 4 + l4 + 16); }
;                 else if (g + 1 < 8) { q0 = *(const f32x4*)(bp + (size_t)rn * ldc * 4 + l4); q1 = *(const f32x4*)(bp + (size_t)rn * ldc * 4 + l4 + 16); }
;                 const f32x4 z0 = gv[bj][0] * ((p0 - mu) * r) + acc[ai][bj][m][0] + cv[bj][0], z1 = gv[bj][1] * ((p1 - mu) * r) + acc[ai][bj][m][1] + cv[bj][1];
;                 *(f32x4*)(op + ro * 4 + l4) = z0; *(f32x4*)(op + ro * 4 + l4 + 16) = z1;
;                 s1 += ((z0[0] + z0[1]) + (z0[2] + z0[3])) + ((z1[0] + z1[1]) + (z1[2] + z1[3]));
;                 s2 += ((z0[0] * z0[0] + z0[1] * z0[1]) + (z0[2] * z0[2] + z0[3] * z0[3])) + ((z1[0] * z1[0] + z1[1] * z1[1]) + (z1[2] * z1[2] + z1[3] * z1[3]));
;                 if (zb) { u32x4 w; w.x = cvt_pk_bf16(z0[0], z0[1]); w.y = cvt_pk_bf16(z0[2], z0[3]); w.z = cvt_pk_bf16(z1[0], z1[1]); w.w = cvt_pk_bf16(z1[2], z1[3]); *(u32x4*)(zp + ro * 2 + l2) = w; }
;                 p0 = q0; p1 = q1; }
;             s1 += __shfl_xor(s1, 16); s2 += __shfl_xor(s2, 16); s1 += __shfl_xor(s1, 32); s2 += __shfl_xor(s2, 32);
;             if (fq == 0) { atomicAdd(osp + 2 * (rr + fr), s1); atomicAdd(osp + 2 * (rr + fr) + 1, s2); }
;             sv_c = sv_n; }
.LBB0_736:
	s_or_b64 exec, exec, s[24:25]
	v_pk_mul_f32 v[102:103], v[114:115], s[54:55] op_sel_hi:[1,0]
	s_mov_b64 s[24:25], 0x30200
	v_fma_f32 v82, -v102, v102, v103
	v_add_f32_e32 v82, 0x3727c5ac, v82
	v_rsq_f32_e32 v100, v82
	v_lshl_add_u64 v[82:83], v[202:203], 0, s[24:25]
	global_load_dwordx2 v[98:99], v[204:205], off offset:1024
	global_load_dwordx4 v[86:89], v[106:107], off offset:512
	s_waitcnt lgkmcnt(0)
	global_load_dwordx4 v[82:85], v[82:83], off offset:16
	s_waitcnt vmcnt(9)
	v_sub_f32_e32 v95, v95, v102
	v_sub_f32_e32 v94, v94, v102
	v_sub_f32_e32 v97, v97, v102
	v_sub_f32_e32 v96, v96, v102
	v_pk_mul_f32 v[96:97], v[100:101], v[96:97] op_sel_hi:[0,1]
	v_pk_mul_f32 v[94:95], v[100:101], v[94:95] op_sel_hi:[0,1]
	s_waitcnt vmcnt(8)
	v_sub_f32_e32 v91, v91, v102
	v_sub_f32_e32 v90, v90, v102
	v_sub_f32_e32 v93, v93, v102
	v_sub_f32_e32 v92, v92, v102
	v_pk_fma_f32 v[78:79], v[170:171], v[94:95], v[78:79]
	v_pk_fma_f32 v[80:81], v[162:163], v[96:97], v[80:81]
	v_pk_mul_f32 v[92:93], v[100:101], v[92:93] op_sel_hi:[0,1]
	v_pk_mul_f32 v[90:91], v[100:101], v[90:91] op_sel_hi:[0,1]
	v_pk_add_f32 v[80:81], v[186:187], v[80:81]
	v_pk_add_f32 v[78:79], v[188:189], v[78:79]
	v_pk_fma_f32 v[74:75], v[196:197], v[90:91], v[74:75]
	v_pk_fma_f32 v[76:77], v[194:195], v[92:93], v[76:77]
	v_pk_add_f32 v[74:75], v[192:193], v[74:75]
	v_pk_add_f32 v[76:77], v[190:191], v[76:77]
	v_add_f32_e32 v90, v78, v79
	v_add_f32_e32 v91, v80, v81
	v_add_f32_e32 v90, v90, v91
	v_add_f32_e32 v91, v74, v75
	v_add_f32_e32 v94, v76, v77
	v_add_f32_e32 v91, v91, v94
	v_add_f32_e32 v90, v90, v91
	v_add_f32_e32 v96, 0, v90
	v_mul_f32_e32 v90, v79, v79
	v_mul_f32_e32 v91, v81, v81
	v_fmac_f32_e32 v90, v78, v78
	v_fmac_f32_e32 v91, v80, v80
	v_add_co_u32_e32 v92, vcc, s1, v200
	v_add_f32_e32 v90, v90, v91
	v_mul_f32_e32 v91, v75, v75
	v_mul_f32_e32 v94, v77, v77
	v_addc_co_u32_e32 v93, vcc, 0, v201, vcc
	v_fmac_f32_e32 v91, v74, v74
	v_fmac_f32_e32 v94, v76, v76
	s_mov_b32 s1, 0x18000
	v_add_f32_e32 v91, v91, v94
	v_add_co_u32_e32 v94, vcc, s1, v198
	s_mov_b32 s1, 0x80000
	s_nop 0
	v_addc_co_u32_e32 v95, vcc, 0, v199, vcc
	v_add_f32_e32 v97, v90, v91
	s_mov_b64 s[24:25], 0x80000
	v_add_co_u32_e32 v90, vcc, s1, v202
	global_store_dwordx4 v[92:93], v[78:81], off nt
	global_store_dwordx4 v[92:93], v[74:77], off offset:16 nt
	v_addc_co_u32_e32 v91, vcc, 0, v203, vcc
	v_cvt_pk_bf16_f32 v78, v78, v79
	v_cvt_pk_bf16_f32 v79, v80, v81
	v_cvt_pk_bf16_f32 v80, v74, v75
	v_cvt_pk_bf16_f32 v81, v76, v77
	global_store_dwordx4 v[94:95], v[78:81], off
	v_lshl_add_u64 v[74:75], v[202:203], 0, s[24:25]
	global_load_dwordx4 v[78:81], v[90:91], off
	s_nop 0
	global_load_dwordx4 v[74:77], v[74:75], off offset:16
	s_waitcnt vmcnt(6)
	v_sub_f32_e32 v87, v87, v102
	v_sub_f32_e32 v86, v86, v102
	v_sub_f32_e32 v89, v89, v102
	v_sub_f32_e32 v88, v88, v102
	v_pk_mul_f32 v[88:89], v[100:101], v[88:89] op_sel_hi:[0,1]
	v_pk_mul_f32 v[86:87], v[100:101], v[86:87] op_sel_hi:[0,1]
	s_waitcnt vmcnt(5)
	v_sub_f32_e32 v83, v83, v102
	v_sub_f32_e32 v82, v82, v102
	v_sub_f32_e32 v85, v85, v102
	v_sub_f32_e32 v84, v84, v102
	v_pk_fma_f32 v[70:71], v[164:165], v[86:87], v[70:71]
	v_pk_fma_f32 v[72:73], v[160:161], v[88:89], v[72:73]
	v_pk_mul_f32 v[84:85], v[100:101], v[84:85] op_sel_hi:[0,1]
	v_pk_mul_f32 v[82:83], v[100:101], v[82:83] op_sel_hi:[0,1]
	v_pk_add_f32 v[72:73], v[174:175], v[72:73]
	v_pk_add_f32 v[70:71], v[176:177], v[70:71]
	v_pk_fma_f32 v[66:67], v[178:179], v[82:83], v[66:67]
	v_pk_fma_f32 v[68:69], v[172:173], v[84:85], v[68:69]
	v_pk_add_f32 v[66:67], v[168:169], v[66:67]
	v_pk_add_f32 v[68:69], v[166:167], v[68:69]
	v_add_f32_e32 v82, v70, v71
	v_add_f32_e32 v83, v72, v73
	v_add_f32_e32 v82, v82, v83
	v_add_f32_e32 v83, v66, v67
	v_add_f32_e32 v84, v68, v69
	v_add_f32_e32 v83, v83, v84
	v_add_f32_e32 v82, v82, v83
	v_mul_f32_e32 v83, v71, v71
	v_mul_f32_e32 v84, v73, v73
	v_fmac_f32_e32 v83, v70, v70
	v_fmac_f32_e32 v84, v72, v72
	v_add_f32_e32 v83, v83, v84
	v_mul_f32_e32 v84, v67, v67
	v_mul_f32_e32 v85, v69, v69
	v_fmac_f32_e32 v84, v66, v66
	v_fmac_f32_e32 v85, v68, v68
	v_add_f32_e32 v84, v84, v85
	v_add_f32_e32 v83, v83, v84
	v_add_f32_e32 v82, v96, v82
	v_add_f32_e32 v83, v97, v83
	global_store_dwordx4 v[92:93], v[70:73], off offset:512 nt
	global_store_dwordx4 v[92:93], v[66:69], off offset:528 nt
	s_nop 0
	v_cvt_pk_bf16_f32 v70, v70, v71
	v_cvt_pk_bf16_f32 v71, v72, v73
	v_cvt_pk_bf16_f32 v72, v66, v67
	ds_bpermute_b32 v66, v133, v82
	ds_bpermute_b32 v67, v133, v83
	v_cvt_pk_bf16_f32 v73, v68, v69
	global_store_dwordx4 v[94:95], v[70:73], off offset:256
	s_waitcnt lgkmcnt(1)
	v_add_f32_e32 v66, v82, v66
	s_waitcnt lgkmcnt(0)
	v_add_f32_e32 v67, v83, v67
	ds_bpermute_b32 v68, v136, v66
	ds_bpermute_b32 v69, v136, v67
	s_and_saveexec_b64 s[24:25], s[40:41]
	s_cbranch_execz .LBB0_738
	s_waitcnt lgkmcnt(1)
	v_add_f32_e32 v66, v66, v68
	s_waitcnt lgkmcnt(0)
	v_add_f32_e32 v67, v67, v69
	global_atomic_add_f32 v137, v66, s[82:83] offset:384
	global_atomic_add_f32 v137, v67, s[82:83] offset:388
; __device__ __forceinline__ unsigned cvt_pk_bf16(float lo, float hi) { unsigned r; asm volatile("v_cvt_pk_bf16_f32 %0, %1, %2" : "=v"(r) : "v"(lo), "v"(hi)); return r; }
; __device__ __forceinline__ void stats_mr(const f32x2 s, float& mu, float& r) { mu = s.x * (1.0f / 1024.0f); const float var = s.y * (1.0f / 1024.0f) - mu * mu; r = __builtin_amdgcn_rsqf(var + 1e-5f); }
;     __device__ __forceinline__ void operator()(const f32x4 (&acc)[2][2][4][2], const Unit& u, int wr, int wc, int fr, int fq) const {
;     ...
;         for (int g = 0; g < 8; ++g) { const int ai = g >> 2, m = g & 3; const int rr = ai * HALF + m * 16, rn = ((g + 1) >> 2) * HALF + ((g + 1) & 3) * 16;
;             f32x2 sv_n = sv_c; if (g + 1 < 8) sv_n = *(const f32x2*)(sp + (size_t)rn * 8 + ls);
;             float mu, r; stats_mr(sv_c, mu, r); float s1 = 0.f, s2 = 0.f;
; #pragma unroll
;             for (int bj = 0; bj < 2; ++bj) { const size_t ro = (size_t)rr * ldc + bj * HALF;
;                 f32x4 q0 = p0, q1 = p1;
;                 if (bj == 0) { q0 = *(const f32x4*)(bp + (ro + HALF) * 4 + l4); q1 = *(const f32x4*)(bp + (ro + HALF) * 4 + l4 + 16); }
;                 else if (g + 1 < 8) { q0 = *(const f32x4*)(bp + (size_t)rn * ldc * 4 + l4); q1 = *(const f32x4*)(bp + (size_t)rn * ldc * 4 + l4 + 16); }
;                 const f32x4 z0 = gv[bj][0] * ((p0 - mu) * r) + acc[ai][bj][m][0] + cv[bj][0], z1 = gv[bj][1] * ((p1 - mu) * r) + acc[ai][bj][m][1] + cv[bj][1];
;                 *(f32x4*)(op + ro * 4 + l4) = z0; *(f32x4*)(op + ro * 4 + l4 + 16) = z1;
;                 s1 += ((z0[0] + z0[1]) + (z0[2] + z0[3])) + ((z1[0] + z1[1]) + (z1[2] + z1[3]));
;                 s2 += ((z0[0] * z0[0] + z0[1] * z0[1]) + (z0[2] * z0[2] + z0[3] * z0[3])) + ((z1[0] * z1[0] + z1[1] * z1[1]) + (z1[2] * z1[2] + z1[3] * z1[3]));
;                 if (zb) { u32x4 w; w.x = cvt_pk_bf16(z0[0], z0[1]); w.y = cvt_pk_bf16(z0[2], z0[3]); w.z = cvt_pk_bf16(z1[0], z1[1]); w.w = cvt_pk_bf16(z1[2], z1[3]); *(u32x4*)(zp + ro * 2 + l2) = w; }
;                 p0 = q0; p1 = q1; }
;             s1 += __shfl_xor(s1, 16); s2 += __shfl_xor(s2, 16); s1 += __shfl_xor(s1, 32); s2 += __shfl_xor(s2, 32);
;             if (fq == 0) { atomicAdd(osp + 2 * (rr + fr), s1); atomicAdd(osp + 2 * (rr + fr) + 1, s2); }
;             sv_c = sv_n; }
.LBB0_738:
	s_or_b64 exec, exec, s[24:25]
	v_pk_mul_f32 v[86:87], v[98:99], s[54:55] op_sel_hi:[1,0]
	s_mov_b64 s[24:25], 0x80200
	v_fma_f32 v66, -v86, v86, v87
	v_add_f32_e32 v66, 0x3727c5ac, v66
	v_rsq_f32_e32 v84, v66
	v_lshl_add_u64 v[66:67], v[202:203], 0, s[24:25]
	global_load_dwordx2 v[82:83], v[204:205], off offset:1152
	global_load_dwordx4 v[70:73], v[90:91], off offset:512
	s_waitcnt lgkmcnt(0)
	global_load_dwordx4 v[66:69], v[66:67], off offset:16
	s_waitcnt vmcnt(9)
	v_sub_f32_e32 v79, v79, v86
	v_sub_f32_e32 v78, v78, v86
	v_sub_f32_e32 v81, v81, v86
	v_sub_f32_e32 v80, v80, v86
	v_pk_mul_f32 v[80:81], v[84:85], v[80:81] op_sel_hi:[0,1]
	v_pk_mul_f32 v[78:79], v[84:85], v[78:79] op_sel_hi:[0,1]
	s_waitcnt vmcnt(8)
	v_sub_f32_e32 v75, v75, v86
	v_sub_f32_e32 v74, v74, v86
	v_sub_f32_e32 v77, v77, v86
	v_sub_f32_e32 v76, v76, v86
	v_pk_fma_f32 v[62:63], v[170:171], v[78:79], v[62:63]
	v_pk_fma_f32 v[64:65], v[162:163], v[80:81], v[64:65]
	v_pk_mul_f32 v[76:77], v[84:85], v[76:77] op_sel_hi:[0,1]
	v_pk_mul_f32 v[74:75], v[84:85], v[74:75] op_sel_hi:[0,1]
	v_pk_add_f32 v[64:65], v[186:187], v[64:65]
	v_pk_add_f32 v[62:63], v[188:189], v[62:63]
	v_pk_fma_f32 v[58:59], v[196:197], v[74:75], v[58:59]
	v_pk_fma_f32 v[60:61], v[194:195], v[76:77], v[60:61]
	v_pk_add_f32 v[58:59], v[192:193], v[58:59]
	v_pk_add_f32 v[60:61], v[190:191], v[60:61]
	v_add_f32_e32 v74, v62, v63
	v_add_f32_e32 v75, v64, v65
	v_add_f32_e32 v74, v74, v75
	v_add_f32_e32 v75, v58, v59
	v_add_f32_e32 v78, v60, v61
	v_add_f32_e32 v75, v75, v78
	v_add_f32_e32 v74, v74, v75
	v_add_f32_e32 v80, 0, v74
	v_mul_f32_e32 v74, v63, v63
	v_mul_f32_e32 v75, v65, v65
	v_fmac_f32_e32 v74, v62, v62
	v_fmac_f32_e32 v75, v64, v64
	v_add_co_u32_e32 v76, vcc, s1, v200
	v_add_f32_e32 v74, v74, v75
	v_mul_f32_e32 v75, v59, v59
	v_mul_f32_e32 v78, v61, v61
	v_addc_co_u32_e32 v77, vcc, 0, v201, vcc
	v_fmac_f32_e32 v75, v58, v58
	v_fmac_f32_e32 v78, v60, v60
	s_mov_b32 s1, 0x40000
	v_add_f32_e32 v75, v75, v78
	v_add_co_u32_e32 v78, vcc, s1, v198
	v_add_f32_e32 v81, v74, v75
	s_nop 0
	v_addc_co_u32_e32 v79, vcc, 0, v199, vcc
	v_add_co_u32_e32 v74, vcc, s5, v202
	global_store_dwordx4 v[76:77], v[62:65], off nt
	global_store_dwordx4 v[76:77], v[58:61], off offset:16 nt
	v_addc_co_u32_e32 v75, vcc, 0, v203, vcc
	v_cvt_pk_bf16_f32 v62, v62, v63
	v_cvt_pk_bf16_f32 v63, v64, v65
	v_cvt_pk_bf16_f32 v64, v58, v59
	v_cvt_pk_bf16_f32 v65, v60, v61
	global_store_dwordx4 v[78:79], v[62:65], off
	v_lshl_add_u64 v[58:59], v[202:203], 0, s[28:29]
	global_load_dwordx4 v[62:65], v[74:75], off
	s_nop 0
	global_load_dwordx4 v[58:61], v[58:59], off offset:16
	s_waitcnt vmcnt(6)
	v_sub_f32_e32 v71, v71, v86
	v_sub_f32_e32 v70, v70, v86
	v_sub_f32_e32 v73, v73, v86
	v_sub_f32_e32 v72, v72, v86
	v_pk_mul_f32 v[72:73], v[84:85], v[72:73] op_sel_hi:[0,1]
	v_pk_mul_f32 v[70:71], v[84:85], v[70:71] op_sel_hi:[0,1]
	s_waitcnt vmcnt(5)
	v_sub_f32_e32 v67, v67, v86
	v_sub_f32_e32 v66, v66, v86
	v_sub_f32_e32 v69, v69, v86
	v_sub_f32_e32 v68, v68, v86
	v_pk_fma_f32 v[54:55], v[164:165], v[70:71], v[54:55]
	v_pk_fma_f32 v[56:57], v[160:161], v[72:73], v[56:57]
	v_pk_mul_f32 v[68:69], v[84:85], v[68:69] op_sel_hi:[0,1]
	v_pk_mul_f32 v[66:67], v[84:85], v[66:67] op_sel_hi:[0,1]
	v_pk_add_f32 v[56:57], v[174:175], v[56:57]
	v_pk_add_f32 v[54:55], v[176:177], v[54:55]
	v_pk_fma_f32 v[50:51], v[178:179], v[66:67], v[50:51]
	v_pk_fma_f32 v[52:53], v[172:173], v[68:69], v[52:53]
	v_pk_add_f32 v[50:51], v[168:169], v[50:51]
	v_pk_add_f32 v[52:53], v[166:167], v[52:53]
	v_add_f32_e32 v66, v54, v55
	v_add_f32_e32 v67, v56, v57
	v_add_f32_e32 v66, v66, v67
	v_add_f32_e32 v67, v50, v51
	v_add_f32_e32 v68, v52, v53
	v_add_f32_e32 v67, v67, v68
	v_add_f32_e32 v66, v66, v67
	v_mul_f32_e32 v67, v55, v55
	v_mul_f32_e32 v68, v57, v57
	v_fmac_f32_e32 v67, v54, v54
	v_fmac_f32_e32 v68, v56, v56
	v_add_f32_e32 v67, v67, v68
	v_mul_f32_e32 v68, v51, v51
	v_mul_f32_e32 v69, v53, v53
	v_fmac_f32_e32 v68, v50, v50
	v_fmac_f32_e32 v69, v52, v52
	v_add_f32_e32 v68, v68, v69
	v_add_f32_e32 v67, v67, v68
	v_add_f32_e32 v66, v80, v66
	v_add_f32_e32 v67, v81, v67
	global_store_dwordx4 v[76:77], v[54:57], off offset:512 nt
	global_store_dwordx4 v[76:77], v[50:53], off offset:528 nt
	s_nop 0
	v_cvt_pk_bf16_f32 v54, v54, v55
	v_cvt_pk_bf16_f32 v55, v56, v57
	v_cvt_pk_bf16_f32 v56, v50, v51
	ds_bpermute_b32 v50, v133, v66
	ds_bpermute_b32 v51, v133, v67
	v_cvt_pk_bf16_f32 v57, v52, v53
	global_store_dwordx4 v[78:79], v[54:57], off offset:256
	s_waitcnt lgkmcnt(1)
	v_add_f32_e32 v50, v66, v50
	s_waitcnt lgkmcnt(0)
	v_add_f32_e32 v51, v67, v51
	ds_bpermute_b32 v52, v136, v50
	ds_bpermute_b32 v53, v136, v51
	s_and_saveexec_b64 s[24:25], s[40:41]
	s_cbranch_execz .LBB0_740
	s_waitcnt lgkmcnt(1)
	v_add_f32_e32 v50, v50, v52
	s_waitcnt lgkmcnt(0)
	v_add_f32_e32 v51, v51, v53
	global_atomic_add_f32 v137, v50, s[82:83] offset:1024
	global_atomic_add_f32 v137, v51, s[82:83] offset:1028
; __device__ __forceinline__ unsigned cvt_pk_bf16(float lo, float hi) { unsigned r; asm volatile("v_cvt_pk_bf16_f32 %0, %1, %2" : "=v"(r) : "v"(lo), "v"(hi)); return r; }
; __device__ __forceinline__ void stats_mr(const f32x2 s, float& mu, float& r) { mu = s.x * (1.0f / 1024.0f); const float var = s.y * (1.0f / 1024.0f) - mu * mu; r = __builtin_amdgcn_rsqf(var + 1e-5f); }
;     __device__ __forceinline__ void operator()(const f32x4 (&acc)[2][2][4][2], const Unit& u, int wr, int wc, int fr, int fq) const {
;     ...
;         for (int g = 0; g < 8; ++g) { const int ai = g >> 2, m = g & 3; const int rr = ai * HALF + m * 16, rn = ((g + 1) >> 2) * HALF + ((g + 1) & 3) * 16;
;             f32x2 sv_n = sv_c; if (g + 1 < 8) sv_n = *(const f32x2*)(sp + (size_t)rn * 8 + ls);
;             float mu, r; stats_mr(sv_c, mu, r); float s1 = 0.f, s2 = 0.f;
; #pragma unroll
;             for (int bj = 0; bj < 2; ++bj) { const size_t ro = (size_t)rr * ldc + bj * HALF;
;                 f32x4 q0 = p0, q1 = p1;
;                 if (bj == 0) { q0 = *(const f32x4*)(bp + (ro + HALF) * 4 + l4); q1 = *(const f32x4*)(bp + (ro + HALF) * 4 + l4 + 16); }
;                 else if (g + 1 < 8) { q0 = *(const f32x4*)(bp + (size_t)rn * ldc * 4 + l4); q1 = *(const f32x4*)(bp + (size_t)rn * ldc * 4 + l4 + 16); }
;                 const f32x4 z0 = gv[bj][0] * ((p0 - mu) * r) + acc[ai][bj][m][0] + cv[bj][0], z1 = gv[bj][1] * ((p1 - mu) * r) + acc[ai][bj][m][1] + cv[bj][1];
;                 *(f32x4*)(op + ro * 4 + l4) = z0; *(f32x4*)(op + ro * 4 + l4 + 16) = z1;
;                 s1 += ((z0[0] + z0[1]) + (z0[2] + z0[3])) + ((z1[0] + z1[1]) + (z1[2] + z1[3]));
;                 s2 += ((z0[0] * z0[0] + z0[1] * z0[1]) + (z0[2] * z0[2] + z0[3] * z0[3])) + ((z1[0] * z1[0] + z1[1] * z1[1]) + (z1[2] * z1[2] + z1[3] * z1[3]));
;                 if (zb) { u32x4 w; w.x = cvt_pk_bf16(z0[0], z0[1]); w.y = cvt_pk_bf16(z0[2], z0[3]); w.z = cvt_pk_bf16(z1[0], z1[1]); w.w = cvt_pk_bf16(z1[2], z1[3]); *(u32x4*)(zp + ro * 2 + l2) = w; }
;                 p0 = q0; p1 = q1; }
;             s1 += __shfl_xor(s1, 16); s2 += __shfl_xor(s2, 16); s1 += __shfl_xor(s1, 32); s2 += __shfl_xor(s2, 32);
;             if (fq == 0) { atomicAdd(osp + 2 * (rr + fr), s1); atomicAdd(osp + 2 * (rr + fr) + 1, s2); }
;             sv_c = sv_n; }
.LBB0_740:
	s_or_b64 exec, exec, s[24:25]
	v_pk_mul_f32 v[70:71], v[82:83], s[54:55] op_sel_hi:[1,0]
	s_mov_b64 s[24:25], 0x90200
	v_fma_f32 v50, -v70, v70, v71
	v_add_f32_e32 v50, 0x3727c5ac, v50
	v_rsq_f32_e32 v68, v50
	v_lshl_add_u64 v[50:51], v[202:203], 0, s[24:25]
	global_load_dwordx2 v[66:67], v[204:205], off offset:1280
	global_load_dwordx4 v[54:57], v[74:75], off offset:512
	s_waitcnt lgkmcnt(0)
	global_load_dwordx4 v[50:53], v[50:51], off offset:16
	s_waitcnt vmcnt(9)
	v_sub_f32_e32 v63, v63, v70
	v_sub_f32_e32 v62, v62, v70
	v_sub_f32_e32 v65, v65, v70
	v_sub_f32_e32 v64, v64, v70
	v_pk_mul_f32 v[64:65], v[68:69], v[64:65] op_sel_hi:[0,1]
	v_pk_mul_f32 v[62:63], v[68:69], v[62:63] op_sel_hi:[0,1]
	s_waitcnt vmcnt(8)
	v_sub_f32_e32 v59, v59, v70
	v_sub_f32_e32 v58, v58, v70
	v_sub_f32_e32 v61, v61, v70
	v_sub_f32_e32 v60, v60, v70
	v_pk_fma_f32 v[46:47], v[170:171], v[62:63], v[46:47]
	v_pk_fma_f32 v[48:49], v[162:163], v[64:65], v[48:49]
	v_pk_mul_f32 v[60:61], v[68:69], v[60:61] op_sel_hi:[0,1]
	v_pk_mul_f32 v[58:59], v[68:69], v[58:59] op_sel_hi:[0,1]
	v_pk_add_f32 v[48:49], v[186:187], v[48:49]
	v_pk_add_f32 v[46:47], v[188:189], v[46:47]
	v_pk_fma_f32 v[42:43], v[196:197], v[58:59], v[42:43]
	v_pk_fma_f32 v[44:45], v[194:195], v[60:61], v[44:45]
	v_pk_add_f32 v[42:43], v[192:193], v[42:43]
	v_pk_add_f32 v[44:45], v[190:191], v[44:45]
	v_add_f32_e32 v58, v46, v47
	v_add_f32_e32 v59, v48, v49
	v_add_f32_e32 v58, v58, v59
	v_add_f32_e32 v59, v42, v43
	v_add_f32_e32 v62, v44, v45
	v_add_f32_e32 v59, v59, v62
	v_add_f32_e32 v58, v58, v59
	v_add_f32_e32 v64, 0, v58
	v_mul_f32_e32 v58, v47, v47
	v_mul_f32_e32 v59, v49, v49
	v_fmac_f32_e32 v58, v46, v46
	v_fmac_f32_e32 v59, v48, v48
	v_add_co_u32_e32 v60, vcc, s5, v200
	v_add_f32_e32 v58, v58, v59
	v_mul_f32_e32 v59, v43, v43
	v_mul_f32_e32 v62, v45, v45
	v_addc_co_u32_e32 v61, vcc, 0, v201, vcc
	v_fmac_f32_e32 v59, v42, v42
	v_fmac_f32_e32 v62, v44, v44
	s_mov_b32 s1, 0x48000
	v_add_f32_e32 v59, v59, v62
	v_add_co_u32_e32 v62, vcc, s1, v198
	s_mov_b32 s1, 0xa0000
	s_nop 0
	v_addc_co_u32_e32 v63, vcc, 0, v199, vcc
	v_add_f32_e32 v65, v58, v59
	s_mov_b64 s[4:5], 0xa0000
	v_add_co_u32_e32 v58, vcc, s1, v202
	global_store_dwordx4 v[60:61], v[46:49], off nt
	global_store_dwordx4 v[60:61], v[42:45], off offset:16 nt
	v_addc_co_u32_e32 v59, vcc, 0, v203, vcc
	v_cvt_pk_bf16_f32 v46, v46, v47
	v_cvt_pk_bf16_f32 v47, v48, v49
	v_cvt_pk_bf16_f32 v48, v42, v43
	v_cvt_pk_bf16_f32 v49, v44, v45
	global_store_dwordx4 v[62:63], v[46:49], off
	v_lshl_add_u64 v[42:43], v[202:203], 0, s[4:5]
	global_load_dwordx4 v[46:49], v[58:59], off
	s_nop 0
	global_load_dwordx4 v[42:45], v[42:43], off offset:16
	s_waitcnt vmcnt(6)
	v_sub_f32_e32 v55, v55, v70
	v_sub_f32_e32 v54, v54, v70
	v_sub_f32_e32 v57, v57, v70
	v_sub_f32_e32 v56, v56, v70
	v_pk_mul_f32 v[56:57], v[68:69], v[56:57] op_sel_hi:[0,1]
	v_pk_mul_f32 v[54:55], v[68:69], v[54:55] op_sel_hi:[0,1]
	s_waitcnt vmcnt(5)
	v_sub_f32_e32 v51, v51, v70
	v_sub_f32_e32 v50, v50, v70
	v_sub_f32_e32 v53, v53, v70
	v_sub_f32_e32 v52, v52, v70
	v_pk_fma_f32 v[38:39], v[164:165], v[54:55], v[38:39]
	v_pk_fma_f32 v[40:41], v[160:161], v[56:57], v[40:41]
	v_pk_mul_f32 v[52:53], v[68:69], v[52:53] op_sel_hi:[0,1]
	v_pk_mul_f32 v[50:51], v[68:69], v[50:51] op_sel_hi:[0,1]
	v_pk_add_f32 v[40:41], v[174:175], v[40:41]
	v_pk_add_f32 v[38:39], v[176:177], v[38:39]
	v_pk_fma_f32 v[34:35], v[178:179], v[50:51], v[34:35]
	v_pk_fma_f32 v[36:37], v[172:173], v[52:53], v[36:37]
	v_pk_add_f32 v[34:35], v[168:169], v[34:35]
	v_pk_add_f32 v[36:37], v[166:167], v[36:37]
	v_add_f32_e32 v50, v38, v39
	v_add_f32_e32 v51, v40, v41
	v_add_f32_e32 v50, v50, v51
	v_add_f32_e32 v51, v34, v35
	v_add_f32_e32 v52, v36, v37
	v_add_f32_e32 v51, v51, v52
	v_add_f32_e32 v50, v50, v51
	v_mul_f32_e32 v51, v39, v39
	v_mul_f32_e32 v52, v41, v41
	v_fmac_f32_e32 v51, v38, v38
	v_fmac_f32_e32 v52, v40, v40
	v_add_f32_e32 v51, v51, v52
	v_mul_f32_e32 v52, v35, v35
	v_mul_f32_e32 v53, v37, v37
	v_fmac_f32_e32 v52, v34, v34
	v_fmac_f32_e32 v53, v36, v36
	v_add_f32_e32 v52, v52, v53
	v_add_f32_e32 v51, v51, v52
	v_add_f32_e32 v50, v64, v50
	v_add_f32_e32 v51, v65, v51
	global_store_dwordx4 v[60:61], v[38:41], off offset:512 nt
	global_store_dwordx4 v[60:61], v[34:37], off offset:528 nt
	s_nop 0
	v_cvt_pk_bf16_f32 v38, v38, v39
	v_cvt_pk_bf16_f32 v39, v40, v41
	v_cvt_pk_bf16_f32 v40, v34, v35
	ds_bpermute_b32 v34, v133, v50
	ds_bpermute_b32 v35, v133, v51
	v_cvt_pk_bf16_f32 v41, v36, v37
	global_store_dwordx4 v[62:63], v[38:41], off offset:256
	s_waitcnt lgkmcnt(1)
	v_add_f32_e32 v34, v50, v34
	s_waitcnt lgkmcnt(0)
	v_add_f32_e32 v35, v51, v35
	ds_bpermute_b32 v36, v136, v34
	ds_bpermute_b32 v37, v136, v35
	s_and_saveexec_b64 s[24:25], s[40:41]
	s_cbranch_execz .LBB0_742
	s_waitcnt lgkmcnt(1)
	v_add_f32_e32 v34, v34, v36
	s_waitcnt lgkmcnt(0)
	v_add_f32_e32 v35, v35, v37
	global_atomic_add_f32 v137, v34, s[82:83] offset:1152
	global_atomic_add_f32 v137, v35, s[82:83] offset:1156
; __device__ __forceinline__ unsigned cvt_pk_bf16(float lo, float hi) { unsigned r; asm volatile("v_cvt_pk_bf16_f32 %0, %1, %2" : "=v"(r) : "v"(lo), "v"(hi)); return r; }
; __device__ __forceinline__ void stats_mr(const f32x2 s, float& mu, float& r) { mu = s.x * (1.0f / 1024.0f); const float var = s.y * (1.0f / 1024.0f) - mu * mu; r = __builtin_amdgcn_rsqf(var + 1e-5f); }
;     __device__ __forceinline__ void operator()(const f32x4 (&acc)[2][2][4][2], const Unit& u, int wr, int wc, int fr, int fq) const {
;     ...
;         for (int g = 0; g < 8; ++g) { const int ai = g >> 2, m = g & 3; const int rr = ai * HALF + m * 16, rn = ((g + 1) >> 2) * HALF + ((g + 1) & 3) * 16;
;             f32x2 sv_n = sv_c; if (g + 1 < 8) sv_n = *(const f32x2*)(sp + (size_t)rn * 8 + ls);
;             float mu, r; stats_mr(sv_c, mu, r); float s1 = 0.f, s2 = 0.f;
; #pragma unroll
;             for (int bj = 0; bj < 2; ++bj) { const size_t ro = (size_t)rr * ldc + bj * HALF;
;                 f32x4 q0 = p0, q1 = p1;
;                 if (bj == 0) { q0 = *(const f32x4*)(bp + (ro + HALF) * 4 + l4); q1 = *(const f32x4*)(bp + (ro + HALF) * 4 + l4 + 16); }
;                 else if (g + 1 < 8) { q0 = *(const f32x4*)(bp + (size_t)rn * ldc * 4 + l4); q1 = *(const f32x4*)(bp + (size_t)rn * ldc * 4 + l4 + 16); }
;                 const f32x4 z0 = gv[bj][0] * ((p0 - mu) * r) + acc[ai][bj][m][0] + cv[bj][0], z1 = gv[bj][1] * ((p1 - mu) * r) + acc[ai][bj][m][1] + cv[bj][1];
;                 *(f32x4*)(op + ro * 4 + l4) = z0; *(f32x4*)(op + ro * 4 + l4 + 16) = z1;
;                 s1 += ((z0[0] + z0[1]) + (z0[2] + z0[3])) + ((z1[0] + z1[1]) + (z1[2] + z1[3]));
;                 s2 += ((z0[0] * z0[0] + z0[1] * z0[1]) + (z0[2] * z0[2] + z0[3] * z0[3])) + ((z1[0] * z1[0] + z1[1] * z1[1]) + (z1[2] * z1[2] + z1[3] * z1[3]));
;                 if (zb) { u32x4 w; w.x = cvt_pk_bf16(z0[0], z0[1]); w.y = cvt_pk_bf16(z0[2], z0[3]); w.z = cvt_pk_bf16(z1[0], z1[1]); w.w = cvt_pk_bf16(z1[2], z1[3]); *(u32x4*)(zp + ro * 2 + l2) = w; }
;                 p0 = q0; p1 = q1; }
;             s1 += __shfl_xor(s1, 16); s2 += __shfl_xor(s2, 16); s1 += __shfl_xor(s1, 32); s2 += __shfl_xor(s2, 32);
;             if (fq == 0) { atomicAdd(osp + 2 * (rr + fr), s1); atomicAdd(osp + 2 * (rr + fr) + 1, s2); }
;             sv_c = sv_n; }
.LBB0_742:
	s_or_b64 exec, exec, s[24:25]
	v_pk_mul_f32 v[54:55], v[66:67], s[54:55] op_sel_hi:[1,0]
	s_mov_b64 s[4:5], 0xa0200
	v_fma_f32 v34, -v54, v54, v55
	v_add_f32_e32 v34, 0x3727c5ac, v34
	v_rsq_f32_e32 v52, v34
	v_lshl_add_u64 v[34:35], v[202:203], 0, s[4:5]
	global_load_dwordx2 v[50:51], v[204:205], off offset:1408
	global_load_dwordx4 v[38:41], v[58:59], off offset:512
	s_waitcnt lgkmcnt(0)
	global_load_dwordx4 v[34:37], v[34:35], off offset:16
	s_waitcnt vmcnt(9)
	v_sub_f32_e32 v47, v47, v54
	v_sub_f32_e32 v46, v46, v54
	v_sub_f32_e32 v49, v49, v54
	v_sub_f32_e32 v48, v48, v54
	v_pk_mul_f32 v[48:49], v[52:53], v[48:49] op_sel_hi:[0,1]
	v_pk_mul_f32 v[46:47], v[52:53], v[46:47] op_sel_hi:[0,1]
	s_waitcnt vmcnt(8)
	v_sub_f32_e32 v43, v43, v54
	v_sub_f32_e32 v42, v42, v54
	v_sub_f32_e32 v45, v45, v54
	v_sub_f32_e32 v44, v44, v54
	v_pk_fma_f32 v[30:31], v[170:171], v[46:47], v[30:31]
	v_pk_fma_f32 v[32:33], v[162:163], v[48:49], v[32:33]
	v_pk_mul_f32 v[44:45], v[52:53], v[44:45] op_sel_hi:[0,1]
	v_pk_mul_f32 v[42:43], v[52:53], v[42:43] op_sel_hi:[0,1]
	v_pk_add_f32 v[32:33], v[186:187], v[32:33]
	v_pk_add_f32 v[30:31], v[188:189], v[30:31]
	v_pk_fma_f32 v[26:27], v[196:197], v[42:43], v[26:27]
	v_pk_fma_f32 v[28:29], v[194:195], v[44:45], v[28:29]
	v_pk_add_f32 v[26:27], v[192:193], v[26:27]
	v_pk_add_f32 v[28:29], v[190:191], v[28:29]
	v_add_f32_e32 v44, v30, v31
	v_add_f32_e32 v45, v32, v33
	v_add_f32_e32 v44, v44, v45
	v_add_f32_e32 v45, v26, v27
	v_add_f32_e32 v46, v28, v29
	v_add_f32_e32 v45, v45, v46
	v_add_f32_e32 v44, v44, v45
	v_add_f32_e32 v48, 0, v44
	v_mul_f32_e32 v44, v31, v31
	v_mul_f32_e32 v45, v33, v33
	v_fmac_f32_e32 v44, v30, v30
	v_fmac_f32_e32 v45, v32, v32
	v_add_f32_e32 v44, v44, v45
	v_mul_f32_e32 v45, v27, v27
	v_mul_f32_e32 v46, v29, v29
	v_add_co_u32_e32 v42, vcc, s1, v200
	v_fmac_f32_e32 v45, v26, v26
	v_fmac_f32_e32 v46, v28, v28
	v_addc_co_u32_e32 v43, vcc, 0, v201, vcc
	v_add_f32_e32 v45, v45, v46
	s_mov_b32 s1, 0x50000
	v_add_f32_e32 v49, v44, v45
	v_add_co_u32_e32 v44, vcc, s1, v198
	s_mov_b32 s1, 0xb0000
	s_nop 0
	v_addc_co_u32_e32 v45, vcc, 0, v199, vcc
	s_mov_b64 s[4:5], 0xb0000
	v_add_co_u32_e32 v46, vcc, s1, v202
	global_store_dwordx4 v[42:43], v[30:33], off nt
	global_store_dwordx4 v[42:43], v[26:29], off offset:16 nt
	v_addc_co_u32_e32 v47, vcc, 0, v203, vcc
	v_cvt_pk_bf16_f32 v30, v30, v31
	v_cvt_pk_bf16_f32 v31, v32, v33
	v_cvt_pk_bf16_f32 v32, v26, v27
	v_cvt_pk_bf16_f32 v33, v28, v29
	global_store_dwordx4 v[44:45], v[30:33], off
	v_lshl_add_u64 v[26:27], v[202:203], 0, s[4:5]
	global_load_dwordx4 v[30:33], v[46:47], off
	s_nop 0
	global_load_dwordx4 v[26:29], v[26:27], off offset:16
	s_waitcnt vmcnt(6)
	v_sub_f32_e32 v39, v39, v54
	v_sub_f32_e32 v38, v38, v54
	v_sub_f32_e32 v41, v41, v54
	v_sub_f32_e32 v40, v40, v54
	v_pk_mul_f32 v[40:41], v[52:53], v[40:41] op_sel_hi:[0,1]
	v_pk_mul_f32 v[38:39], v[52:53], v[38:39] op_sel_hi:[0,1]
	s_waitcnt vmcnt(5)
	v_sub_f32_e32 v35, v35, v54
	v_sub_f32_e32 v34, v34, v54
	v_sub_f32_e32 v37, v37, v54
	v_sub_f32_e32 v36, v36, v54
	v_pk_fma_f32 v[22:23], v[164:165], v[38:39], v[22:23]
	v_pk_fma_f32 v[24:25], v[160:161], v[40:41], v[24:25]
	v_pk_mul_f32 v[36:37], v[52:53], v[36:37] op_sel_hi:[0,1]
	v_pk_mul_f32 v[34:35], v[52:53], v[34:35] op_sel_hi:[0,1]
	v_pk_add_f32 v[24:25], v[174:175], v[24:25]
	v_pk_add_f32 v[22:23], v[176:177], v[22:23]
	v_pk_fma_f32 v[18:19], v[178:179], v[34:35], v[18:19]
	v_pk_fma_f32 v[20:21], v[172:173], v[36:37], v[20:21]
	v_pk_add_f32 v[18:19], v[168:169], v[18:19]
	v_pk_add_f32 v[20:21], v[166:167], v[20:21]
	v_add_f32_e32 v34, v22, v23
	v_add_f32_e32 v35, v24, v25
	v_add_f32_e32 v34, v34, v35
	v_add_f32_e32 v35, v18, v19
	v_add_f32_e32 v36, v20, v21
	v_add_f32_e32 v35, v35, v36
	v_add_f32_e32 v34, v34, v35
	v_mul_f32_e32 v35, v23, v23
	v_mul_f32_e32 v36, v25, v25
	v_fmac_f32_e32 v35, v22, v22
	v_fmac_f32_e32 v36, v24, v24
	v_add_f32_e32 v35, v35, v36
	v_mul_f32_e32 v36, v19, v19
	v_mul_f32_e32 v37, v21, v21
	v_fmac_f32_e32 v36, v18, v18
	v_fmac_f32_e32 v37, v20, v20
	v_add_f32_e32 v36, v36, v37
	v_add_f32_e32 v35, v35, v36
	v_add_f32_e32 v34, v48, v34
	v_add_f32_e32 v35, v49, v35
	global_store_dwordx4 v[42:43], v[22:25], off offset:512 nt
	global_store_dwordx4 v[42:43], v[18:21], off offset:528 nt
	s_nop 0
	v_cvt_pk_bf16_f32 v22, v22, v23
	v_cvt_pk_bf16_f32 v23, v24, v25
	v_cvt_pk_bf16_f32 v24, v18, v19
	ds_bpermute_b32 v18, v133, v34
	ds_bpermute_b32 v19, v133, v35
	v_cvt_pk_bf16_f32 v25, v20, v21
	global_store_dwordx4 v[44:45], v[22:25], off offset:256
	s_waitcnt lgkmcnt(1)
	v_add_f32_e32 v18, v34, v18
	s_waitcnt lgkmcnt(0)
	v_add_f32_e32 v19, v35, v19
	ds_bpermute_b32 v20, v136, v18
	ds_bpermute_b32 v21, v136, v19
	s_and_saveexec_b64 s[24:25], s[40:41]
	s_cbranch_execz .LBB0_744
	s_waitcnt lgkmcnt(1)
	v_add_f32_e32 v18, v18, v20
	s_waitcnt lgkmcnt(0)
	v_add_f32_e32 v19, v19, v21
	global_atomic_add_f32 v137, v18, s[82:83] offset:1280
	global_atomic_add_f32 v137, v19, s[82:83] offset:1284
; __device__ __forceinline__ unsigned cvt_pk_bf16(float lo, float hi) { unsigned r; asm volatile("v_cvt_pk_bf16_f32 %0, %1, %2" : "=v"(r) : "v"(lo), "v"(hi)); return r; }
; __device__ __forceinline__ void stats_mr(const f32x2 s, float& mu, float& r) { mu = s.x * (1.0f / 1024.0f); const float var = s.y * (1.0f / 1024.0f) - mu * mu; r = __builtin_amdgcn_rsqf(var + 1e-5f); }
;     __device__ __forceinline__ void operator()(const f32x4 (&acc)[2][2][4][2], const Unit& u, int wr, int wc, int fr, int fq) const {
;     ...
;         for (int g = 0; g < 8; ++g) { const int ai = g >> 2, m = g & 3; const int rr = ai * HALF + m * 16, rn = ((g + 1) >> 2) * HALF + ((g + 1) & 3) * 16;
;             f32x2 sv_n = sv_c; if (g + 1 < 8) sv_n = *(const f32x2*)(sp + (size_t)rn * 8 + ls);
;             float mu, r; stats_mr(sv_c, mu, r); float s1 = 0.f, s2 = 0.f;
; #pragma unroll
;             for (int bj = 0; bj < 2; ++bj) { const size_t ro = (size_t)rr * ldc + bj * HALF;
;                 f32x4 q0 = p0, q1 = p1;
;                 if (bj == 0) { q0 = *(const f32x4*)(bp + (ro + HALF) * 4 + l4); q1 = *(const f32x4*)(bp + (ro + HALF) * 4 + l4 + 16); }
;                 else if (g + 1 < 8) { q0 = *(const f32x4*)(bp + (size_t)rn * ldc * 4 + l4); q1 = *(const f32x4*)(bp + (size_t)rn * ldc * 4 + l4 + 16); }
;                 const f32x4 z0 = gv[bj][0] * ((p0 - mu) * r) + acc[ai][bj][m][0] + cv[bj][0], z1 = gv[bj][1] * ((p1 - mu) * r) + acc[ai][bj][m][1] + cv[bj][1];
;                 *(f32x4*)(op + ro * 4 + l4) = z0; *(f32x4*)(op + ro * 4 + l4 + 16) = z1;
;                 s1 += ((z0[0] + z0[1]) + (z0[2] + z0[3])) + ((z1[0] + z1[1]) + (z1[2] + z1[3]));
;                 s2 += ((z0[0] * z0[0] + z0[1] * z0[1]) + (z0[2] * z0[2] + z0[3] * z0[3])) + ((z1[0] * z1[0] + z1[1] * z1[1]) + (z1[2] * z1[2] + z1[3] * z1[3]));
;                 if (zb) { u32x4 w; w.x = cvt_pk_bf16(z0[0], z0[1]); w.y = cvt_pk_bf16(z0[2], z0[3]); w.z = cvt_pk_bf16(z1[0], z1[1]); w.w = cvt_pk_bf16(z1[2], z1[3]); *(u32x4*)(zp + ro * 2 + l2) = w; }
;                 p0 = q0; p1 = q1; }
;             s1 += __shfl_xor(s1, 16); s2 += __shfl_xor(s2, 16); s1 += __shfl_xor(s1, 32); s2 += __shfl_xor(s2, 32);
;             if (fq == 0) { atomicAdd(osp + 2 * (rr + fr), s1); atomicAdd(osp + 2 * (rr + fr) + 1, s2); }
;             sv_c = sv_n; }
.LBB0_744:
	s_or_b64 exec, exec, s[24:25]
	s_mov_b64 s[4:5], 0xb0200
	s_waitcnt lgkmcnt(0)
	global_load_dwordx4 v[18:21], v[46:47], off offset:512
	v_lshl_add_u64 v[22:23], v[202:203], 0, s[4:5]
	global_load_dwordx4 v[22:25], v[22:23], off offset:16
	v_pk_mul_f32 v[34:35], v[50:51], s[54:55] op_sel_hi:[1,0]
	v_add_co_u32_e32 v36, vcc, s1, v200
	v_fma_f32 v35, -v34, v34, v35
	v_add_f32_e32 v35, 0x3727c5ac, v35
	v_rsq_f32_e32 v40, v35
	s_waitcnt vmcnt(8)
	v_sub_f32_e32 v31, v31, v34
	v_sub_f32_e32 v30, v30, v34
	v_sub_f32_e32 v33, v33, v34
	v_sub_f32_e32 v32, v32, v34
	s_waitcnt vmcnt(7)
	v_sub_f32_e32 v27, v27, v34
	v_sub_f32_e32 v26, v26, v34
	v_sub_f32_e32 v29, v29, v34
	v_sub_f32_e32 v28, v28, v34
	v_pk_mul_f32 v[32:33], v[40:41], v[32:33] op_sel_hi:[0,1]
	v_pk_mul_f32 v[30:31], v[40:41], v[30:31] op_sel_hi:[0,1]
	v_pk_mul_f32 v[28:29], v[40:41], v[28:29] op_sel_hi:[0,1]
	v_pk_mul_f32 v[26:27], v[40:41], v[26:27] op_sel_hi:[0,1]
	v_pk_fma_f32 v[14:15], v[170:171], v[30:31], v[14:15]
	v_pk_fma_f32 v[16:17], v[162:163], v[32:33], v[16:17]
	v_pk_fma_f32 v[26:27], v[196:197], v[26:27], v[10:11]
	v_pk_fma_f32 v[28:29], v[194:195], v[28:29], v[12:13]
	v_pk_add_f32 v[12:13], v[186:187], v[16:17]
	v_pk_add_f32 v[10:11], v[188:189], v[14:15]
	v_pk_add_f32 v[16:17], v[190:191], v[28:29]
	v_pk_add_f32 v[14:15], v[192:193], v[26:27]
	v_addc_co_u32_e32 v37, vcc, 0, v201, vcc
	s_mov_b32 s1, 0x58000
	v_add_f32_e32 v30, v10, v11
	v_add_f32_e32 v31, v12, v13
	v_add_f32_e32 v32, v14, v15
	v_add_f32_e32 v33, v16, v17
	v_mul_f32_e32 v35, v11, v11
	v_mul_f32_e32 v41, v13, v13
	v_mul_f32_e32 v42, v15, v15
	v_mul_f32_e32 v43, v17, v17
	v_add_co_u32_e32 v38, vcc, s1, v198
	global_store_dwordx4 v[36:37], v[10:13], off nt
	global_store_dwordx4 v[36:37], v[14:17], off offset:16 nt
	v_cvt_pk_bf16_f32 v26, v10, v11
	v_cvt_pk_bf16_f32 v27, v12, v13
	v_fmac_f32_e32 v35, v10, v10
	v_add_f32_e32 v11, v30, v31
	v_add_f32_e32 v13, v32, v33
	v_fmac_f32_e32 v41, v12, v12
	v_fmac_f32_e32 v42, v14, v14
	v_fmac_f32_e32 v43, v16, v16
	v_addc_co_u32_e32 v39, vcc, 0, v199, vcc
	v_add_f32_e32 v10, v11, v13
	v_add_f32_e32 v11, v35, v41
	v_add_f32_e32 v12, v42, v43
	v_cvt_pk_bf16_f32 v28, v14, v15
	v_cvt_pk_bf16_f32 v29, v16, v17
	global_store_dwordx4 v[38:39], v[26:29], off
	s_waitcnt vmcnt(4)
	v_sub_f32_e32 v13, v21, v34
	v_add_f32_e32 v26, 0, v10
	v_add_f32_e32 v27, v11, v12
	v_sub_f32_e32 v11, v19, v34
	v_sub_f32_e32 v10, v18, v34
	v_sub_f32_e32 v12, v20, v34
	v_pk_mul_f32 v[12:13], v[40:41], v[12:13] op_sel_hi:[0,1]
	v_pk_mul_f32 v[10:11], v[40:41], v[10:11] op_sel_hi:[0,1]
	s_waitcnt vmcnt(3)
	v_sub_f32_e32 v15, v23, v34
	v_sub_f32_e32 v14, v22, v34
	v_sub_f32_e32 v17, v25, v34
	v_sub_f32_e32 v16, v24, v34
	v_pk_fma_f32 v[6:7], v[164:165], v[10:11], v[6:7]
	v_pk_fma_f32 v[8:9], v[160:161], v[12:13], v[8:9]
	v_pk_mul_f32 v[10:11], v[40:41], v[16:17] op_sel_hi:[0,1]
	v_pk_mul_f32 v[12:13], v[40:41], v[14:15] op_sel_hi:[0,1]
	v_pk_add_f32 v[8:9], v[174:175], v[8:9]
	v_pk_add_f32 v[6:7], v[176:177], v[6:7]
	v_pk_fma_f32 v[2:3], v[178:179], v[12:13], v[2:3]
	v_pk_fma_f32 v[4:5], v[172:173], v[10:11], v[4:5]
	v_pk_add_f32 v[10:11], v[168:169], v[2:3]
	v_pk_add_f32 v[12:13], v[166:167], v[4:5]
	v_add_f32_e32 v2, v6, v7
	v_add_f32_e32 v3, v8, v9
	v_add_f32_e32 v2, v2, v3
	v_add_f32_e32 v3, v10, v11
	v_add_f32_e32 v4, v12, v13
	v_add_f32_e32 v3, v3, v4
	v_add_f32_e32 v2, v2, v3
	v_mul_f32_e32 v3, v7, v7
	v_mul_f32_e32 v4, v9, v9
	v_fmac_f32_e32 v3, v6, v6
	v_fmac_f32_e32 v4, v8, v8
	v_add_f32_e32 v3, v3, v4
	v_mul_f32_e32 v4, v11, v11
	v_mul_f32_e32 v5, v13, v13
	v_fmac_f32_e32 v4, v10, v10
	v_fmac_f32_e32 v5, v12, v12
	v_add_f32_e32 v4, v4, v5
	v_add_f32_e32 v3, v3, v4
	v_add_f32_e32 v2, v26, v2
	v_add_f32_e32 v3, v27, v3
	ds_bpermute_b32 v4, v133, v2
	ds_bpermute_b32 v5, v133, v3
	global_store_dwordx4 v[36:37], v[6:9], off offset:512 nt
	global_store_dwordx4 v[36:37], v[10:13], off offset:528 nt
	s_waitcnt lgkmcnt(1)
	v_add_f32_e32 v2, v2, v4
	s_waitcnt lgkmcnt(0)
	v_add_f32_e32 v3, v3, v5
	ds_bpermute_b32 v4, v136, v2
	ds_bpermute_b32 v5, v136, v3
	v_cvt_pk_bf16_f32 v6, v6, v7
	v_cvt_pk_bf16_f32 v7, v8, v9
	v_cvt_pk_bf16_f32 v8, v10, v11
	v_cvt_pk_bf16_f32 v9, v12, v13
	global_store_dwordx4 v[38:39], v[6:9], off offset:256
	s_and_saveexec_b64 s[24:25], s[40:41]
	s_cbranch_execz .LBB0_746
	s_waitcnt lgkmcnt(1)
	v_add_f32_e32 v2, v2, v4
	s_waitcnt lgkmcnt(0)
	v_add_f32_e32 v3, v3, v5
	global_atomic_add_f32 v137, v2, s[82:83] offset:1408
	global_atomic_add_f32 v137, v3, s[82:83] offset:1412

; __device__ __forceinline__ unsigned cvt_pk_bf16(float lo, float hi) { unsigned r; asm volatile("v_cvt_pk_bf16_f32 %0, %1, %2" : "=v"(r) : "v"(lo), "v"(hi)); return r; }
; __device__ __forceinline__ void stats_mr(const f32x2 s, float& mu, float& r) { mu = s.x * (1.0f / 1024.0f); const float var = s.y * (1.0f / 1024.0f) - mu * mu; r = __builtin_amdgcn_rsqf(var + 1e-5f); }
;     __device__ __forceinline__ void operator()(const f32x4 (&acc)[2][2][4][2], const Unit& u, int wr, int wc, int fr, int fq) const {
;     ...
;         for (int g = 0; g < 8; ++g) { const int ai = g >> 2, m = g & 3; const int rr = ai * HALF + m * 16, rn = ((g + 1) >> 2) * HALF + ((g + 1) & 3) * 16;
;             f32x2 sv_n = sv_c; if (g + 1 < 8) sv_n = *(const f32x2*)(sp + (size_t)rn * 8 + ls);
;             float mu, r; stats_mr(sv_c, mu, r); float s1 = 0.f, s2 = 0.f;
; #pragma unroll
;             for (int bj = 0; bj < 2; ++bj) { const size_t ro = (size_t)rr * ldc + bj * HALF;
;                 f32x4 q0 = p0, q1 = p1;
;                 if (bj == 0) { q0 = *(const f32x4*)(bp + (ro + HALF) * 4 + l4); q1 = *(const f32x4*)(bp + (ro + HALF) * 4 + l4 + 16); }
;                 else if (g + 1 < 8) { q0 = *(const f32x4*)(bp + (size_t)rn * ldc * 4 + l4); q1 = *(const f32x4*)(bp + (size_t)rn * ldc * 4 + l4 + 16); }
;                 const f32x4 z0 = gv[bj][0] * ((p0 - mu) * r) + acc[ai][bj][m][0] + cv[bj][0], z1 = gv[bj][1] * ((p1 - mu) * r) + acc[ai][bj][m][1] + cv[bj][1];
;                 *(f32x4*)(op + ro * 4 + l4) = z0; *(f32x4*)(op + ro * 4 + l4 + 16) = z1;
;                 s1 += ((z0[0] + z0[1]) + (z0[2] + z0[3])) + ((z1[0] + z1[1]) + (z1[2] + z1[3]));
;                 s2 += ((z0[0] * z0[0] + z0[1] * z0[1]) + (z0[2] * z0[2] + z0[3] * z0[3])) + ((z1[0] * z1[0] + z1[1] * z1[1]) + (z1[2] * z1[2] + z1[3] * z1[3]));
;                 if (zb) { u32x4 w; w.x = cvt_pk_bf16(z0[0], z0[1]); w.y = cvt_pk_bf16(z0[2], z0[3]); w.z = cvt_pk_bf16(z1[0], z1[1]); w.w = cvt_pk_bf16(z1[2], z1[3]); *(u32x4*)(zp + ro * 2 + l2) = w; }
.LBB0_980:
	s_or_b64 exec, exec, s[24:25]
	s_mov_b64 s[4:5], 0x10200
	global_load_dwordx2 v[150:151], v[212:213], off offset:256
	v_lshl_add_u64 v[114:115], v[206:207], 0, s[4:5]
	global_load_dwordx4 v[126:129], v[220:221], off offset:512
	global_load_dwordx4 v[122:125], v[114:115], off offset:16
	v_pk_mul_f32 v[156:157], v[214:215], s[54:55] op_sel_hi:[1,0]
	s_nop 0
	v_fma_f32 v114, -v156, v156, v157
	v_add_f32_e32 v114, 0x3727c5ac, v114
	v_rsq_f32_e32 v154, v114
	s_waitcnt vmcnt(8)
	v_sub_f32_e32 v115, v135, v156
	v_sub_f32_e32 v114, v134, v156
	s_waitcnt lgkmcnt(0)
	v_sub_f32_e32 v117, v137, v156
	v_pk_mul_f32 v[114:115], v[154:155], v[114:115] op_sel_hi:[0,1]
	v_sub_f32_e32 v116, v136, v156
	v_pk_fma_f32 v[110:111], v[202:203], v[114:115], v[110:111]
	s_waitcnt vmcnt(7)
	v_sub_f32_e32 v115, v131, v156
	v_sub_f32_e32 v114, v130, v156
	v_pk_mul_f32 v[116:117], v[154:155], v[116:117] op_sel_hi:[0,1]
	v_pk_mul_f32 v[114:115], v[154:155], v[114:115] op_sel_hi:[0,1]
	v_pk_fma_f32 v[112:113], v[196:197], v[116:117], v[112:113]
	v_sub_f32_e32 v117, v133, v156
	v_sub_f32_e32 v116, v132, v156
	v_pk_fma_f32 v[106:107], v[194:195], v[114:115], v[106:107]
	v_pk_mul_f32 v[116:117], v[154:155], v[116:117] op_sel_hi:[0,1]
	v_pk_add_f32 v[114:115], v[190:191], v[106:107]
	v_add_co_u32_e32 v106, vcc, 0x10000, v206
	v_pk_fma_f32 v[108:109], v[192:193], v[116:117], v[108:109]
	s_nop 0
	v_addc_co_u32_e32 v107, vcc, 0, v207, vcc
	v_pk_add_f32 v[112:113], v[198:199], v[112:113]
	v_pk_add_f32 v[110:111], v[200:201], v[110:111]
	v_pk_add_f32 v[116:117], v[188:189], v[108:109]
	s_and_b64 vcc, exec, s[42:43]
	global_store_dwordx4 v[152:153], v[110:113], off nt
	global_store_dwordx4 v[106:107], v[114:117], off offset:16 nt
	s_cbranch_vccnz .LBB0_982
	v_add_co_u32_e32 v118, vcc, 0x8000, v204
	v_cvt_pk_bf16_f32 v106, v110, v111
	v_cvt_pk_bf16_f32 v107, v112, v113
	v_cvt_pk_bf16_f32 v108, v114, v115
	v_cvt_pk_bf16_f32 v109, v116, v117
	s_nop 1
	v_addc_co_u32_e32 v119, vcc, 0, v205, vcc
	global_store_dwordx4 v[118:119], v[106:109], off

; __device__ __forceinline__ unsigned cvt_pk_bf16(float lo, float hi) { unsigned r; asm volatile("v_cvt_pk_bf16_f32 %0, %1, %2" : "=v"(r) : "v"(lo), "v"(hi)); return r; }
; __device__ __forceinline__ void stats_mr(const f32x2 s, float& mu, float& r) { mu = s.x * (1.0f / 1024.0f); const float var = s.y * (1.0f / 1024.0f) - mu * mu; r = __builtin_amdgcn_rsqf(var + 1e-5f); }
;     __device__ __forceinline__ void operator()(const f32x4 (&acc)[2][2][4][2], const Unit& u, int wr, int wc, int fr, int fq) const {
;     ...
;         for (int g = 0; g < 8; ++g) { const int ai = g >> 2, m = g & 3; const int rr = ai * HALF + m * 16, rn = ((g + 1) >> 2) * HALF + ((g + 1) & 3) * 16;
;             f32x2 sv_n = sv_c; if (g + 1 < 8) sv_n = *(const f32x2*)(sp + (size_t)rn * 8 + ls);
;             float mu, r; stats_mr(sv_c, mu, r); float s1 = 0.f, s2 = 0.f;
; #pragma unroll
;             for (int bj = 0; bj < 2; ++bj) { const size_t ro = (size_t)rr * ldc + bj * HALF;
;                 f32x4 q0 = p0, q1 = p1;
;                 if (bj == 0) { q0 = *(const f32x4*)(bp + (ro + HALF) * 4 + l4); q1 = *(const f32x4*)(bp + (ro + HALF) * 4 + l4 + 16); }
;                 else if (g + 1 < 8) { q0 = *(const f32x4*)(bp + (size_t)rn * ldc * 4 + l4); q1 = *(const f32x4*)(bp + (size_t)rn * ldc * 4 + l4 + 16); }
;                 const f32x4 z0 = gv[bj][0] * ((p0 - mu) * r) + acc[ai][bj][m][0] + cv[bj][0], z1 = gv[bj][1] * ((p1 - mu) * r) + acc[ai][bj][m][1] + cv[bj][1];
;                 *(f32x4*)(op + ro * 4 + l4) = z0; *(f32x4*)(op + ro * 4 + l4 + 16) = z1;
;                 s1 += ((z0[0] + z0[1]) + (z0[2] + z0[3])) + ((z1[0] + z1[1]) + (z1[2] + z1[3]));
;                 s2 += ((z0[0] * z0[0] + z0[1] * z0[1]) + (z0[2] * z0[2] + z0[3] * z0[3])) + ((z1[0] * z1[0] + z1[1] * z1[1]) + (z1[2] * z1[2] + z1[3] * z1[3]));
;                 if (zb) { u32x4 w; w.x = cvt_pk_bf16(z0[0], z0[1]); w.y = cvt_pk_bf16(z0[2], z0[3]); w.z = cvt_pk_bf16(z1[0], z1[1]); w.w = cvt_pk_bf16(z1[2], z1[3]); *(u32x4*)(zp + ro * 2 + l2) = w; }
.LBB0_986:
	s_or_b64 exec, exec, s[24:25]
	s_mov_b64 s[4:5], 0x20200
	v_lshl_add_u64 v[98:99], v[206:207], 0, s[4:5]
	s_mov_b32 s4, 0x20000
	s_waitcnt lgkmcnt(1)
	v_add_co_u32_e32 v100, vcc, s4, v206
	global_load_dwordx2 v[122:123], v[212:213], off offset:384
	s_waitcnt lgkmcnt(0)
	v_addc_co_u32_e32 v101, vcc, 0, v207, vcc
	global_load_dwordx4 v[114:117], v[100:101], off offset:512
	global_load_dwordx4 v[110:113], v[98:99], off offset:16
	v_pk_mul_f32 v[126:127], v[150:151], s[54:55] op_sel_hi:[1,0]
	s_nop 0
	v_fma_f32 v98, -v126, v126, v127
	v_add_f32_e32 v98, 0x3727c5ac, v98
	v_rsq_f32_e32 v124, v98
	s_waitcnt vmcnt(8)
	v_sub_f32_e32 v99, v119, v126
	v_sub_f32_e32 v98, v118, v126
	v_sub_f32_e32 v101, v121, v126
	v_pk_mul_f32 v[98:99], v[124:125], v[98:99] op_sel_hi:[0,1]
	v_sub_f32_e32 v100, v120, v126
	v_pk_fma_f32 v[94:95], v[202:203], v[98:99], v[94:95]
	s_waitcnt vmcnt(7)
	v_sub_f32_e32 v99, v107, v126
	v_sub_f32_e32 v98, v106, v126
	v_pk_mul_f32 v[100:101], v[124:125], v[100:101] op_sel_hi:[0,1]
	v_pk_mul_f32 v[98:99], v[124:125], v[98:99] op_sel_hi:[0,1]
	v_pk_fma_f32 v[96:97], v[196:197], v[100:101], v[96:97]
	v_sub_f32_e32 v101, v109, v126
	v_sub_f32_e32 v100, v108, v126
	v_pk_fma_f32 v[90:91], v[194:195], v[98:99], v[90:91]
	v_pk_mul_f32 v[100:101], v[124:125], v[100:101] op_sel_hi:[0,1]
	v_pk_add_f32 v[102:103], v[190:191], v[90:91]
	v_add_co_u32_e32 v90, vcc, 0x20000, v206
	v_pk_fma_f32 v[92:93], v[192:193], v[100:101], v[92:93]
	s_nop 0
	v_addc_co_u32_e32 v91, vcc, 0, v207, vcc
	v_pk_add_f32 v[96:97], v[198:199], v[96:97]
	v_pk_add_f32 v[94:95], v[200:201], v[94:95]
	v_pk_add_f32 v[104:105], v[188:189], v[92:93]
	s_and_b64 vcc, exec, s[42:43]
	global_store_dwordx4 v[130:131], v[94:97], off nt
	global_store_dwordx4 v[90:91], v[102:105], off offset:16 nt
	s_cbranch_vccnz .LBB0_988
	v_add_co_u32_e32 v98, vcc, 0x10000, v204
	v_cvt_pk_bf16_f32 v90, v94, v95
	v_cvt_pk_bf16_f32 v91, v96, v97
	v_cvt_pk_bf16_f32 v92, v102, v103
	v_cvt_pk_bf16_f32 v93, v104, v105
	s_nop 1
	v_addc_co_u32_e32 v99, vcc, 0, v205, vcc
	global_store_dwordx4 v[98:99], v[90:93], off

; __device__ __forceinline__ unsigned cvt_pk_bf16(float lo, float hi) { unsigned r; asm volatile("v_cvt_pk_bf16_f32 %0, %1, %2" : "=v"(r) : "v"(lo), "v"(hi)); return r; }
; __device__ __forceinline__ void stats_mr(const f32x2 s, float& mu, float& r) { mu = s.x * (1.0f / 1024.0f); const float var = s.y * (1.0f / 1024.0f) - mu * mu; r = __builtin_amdgcn_rsqf(var + 1e-5f); }
;     __device__ __forceinline__ void operator()(const f32x4 (&acc)[2][2][4][2], const Unit& u, int wr, int wc, int fr, int fq) const {
;     ...
;         for (int g = 0; g < 8; ++g) { const int ai = g >> 2, m = g & 3; const int rr = ai * HALF + m * 16, rn = ((g + 1) >> 2) * HALF + ((g + 1) & 3) * 16;
;             f32x2 sv_n = sv_c; if (g + 1 < 8) sv_n = *(const f32x2*)(sp + (size_t)rn * 8 + ls);
;             float mu, r; stats_mr(sv_c, mu, r); float s1 = 0.f, s2 = 0.f;
; #pragma unroll
;             for (int bj = 0; bj < 2; ++bj) { const size_t ro = (size_t)rr * ldc + bj * HALF;
;                 f32x4 q0 = p0, q1 = p1;
;                 if (bj == 0) { q0 = *(const f32x4*)(bp + (ro + HALF) * 4 + l4); q1 = *(const f32x4*)(bp + (ro + HALF) * 4 + l4 + 16); }
;                 else if (g + 1 < 8) { q0 = *(const f32x4*)(bp + (size_t)rn * ldc * 4 + l4); q1 = *(const f32x4*)(bp + (size_t)rn * ldc * 4 + l4 + 16); }
;                 const f32x4 z0 = gv[bj][0] * ((p0 - mu) * r) + acc[ai][bj][m][0] + cv[bj][0], z1 = gv[bj][1] * ((p1 - mu) * r) + acc[ai][bj][m][1] + cv[bj][1];
;                 *(f32x4*)(op + ro * 4 + l4) = z0; *(f32x4*)(op + ro * 4 + l4 + 16) = z1;
;                 s1 += ((z0[0] + z0[1]) + (z0[2] + z0[3])) + ((z1[0] + z1[1]) + (z1[2] + z1[3]));
;                 s2 += ((z0[0] * z0[0] + z0[1] * z0[1]) + (z0[2] * z0[2] + z0[3] * z0[3])) + ((z1[0] * z1[0] + z1[1] * z1[1]) + (z1[2] * z1[2] + z1[3] * z1[3]));
;                 if (zb) { u32x4 w; w.x = cvt_pk_bf16(z0[0], z0[1]); w.y = cvt_pk_bf16(z0[2], z0[3]); w.z = cvt_pk_bf16(z1[0], z1[1]); w.w = cvt_pk_bf16(z1[2], z1[3]); *(u32x4*)(zp + ro * 2 + l2) = w; }
.LBB0_992:
	s_or_b64 exec, exec, s[24:25]
	s_mov_b64 s[4:5], 0x30200
	v_lshl_add_u64 v[82:83], v[206:207], 0, s[4:5]
	s_mov_b32 s4, 0x30000
	s_waitcnt lgkmcnt(1)
	v_add_co_u32_e32 v84, vcc, s4, v206
	global_load_dwordx2 v[106:107], v[212:213], off offset:1024
	s_waitcnt lgkmcnt(0)
	v_addc_co_u32_e32 v85, vcc, 0, v207, vcc
	global_load_dwordx4 v[102:105], v[84:85], off offset:512
	global_load_dwordx4 v[94:97], v[82:83], off offset:16
	v_pk_mul_f32 v[112:113], v[122:123], s[54:55] op_sel_hi:[1,0]
	s_nop 0
	v_fma_f32 v82, -v112, v112, v113
	v_add_f32_e32 v82, 0x3727c5ac, v82
	v_rsq_f32_e32 v110, v82
	s_waitcnt vmcnt(8)
	v_sub_f32_e32 v83, v99, v112
	v_sub_f32_e32 v82, v98, v112
	v_sub_f32_e32 v85, v101, v112
	v_pk_mul_f32 v[82:83], v[110:111], v[82:83] op_sel_hi:[0,1]
	v_sub_f32_e32 v84, v100, v112
	v_pk_fma_f32 v[78:79], v[202:203], v[82:83], v[78:79]
	s_waitcnt vmcnt(7)
	v_sub_f32_e32 v83, v91, v112
	v_sub_f32_e32 v82, v90, v112
	v_pk_mul_f32 v[84:85], v[110:111], v[84:85] op_sel_hi:[0,1]
	v_pk_mul_f32 v[82:83], v[110:111], v[82:83] op_sel_hi:[0,1]
	v_pk_fma_f32 v[80:81], v[196:197], v[84:85], v[80:81]
	v_sub_f32_e32 v85, v93, v112
	v_sub_f32_e32 v84, v92, v112
	v_pk_fma_f32 v[74:75], v[194:195], v[82:83], v[74:75]
	v_pk_mul_f32 v[84:85], v[110:111], v[84:85] op_sel_hi:[0,1]
	v_pk_add_f32 v[86:87], v[190:191], v[74:75]
	v_add_co_u32_e32 v74, vcc, 0x30000, v206
	v_pk_fma_f32 v[76:77], v[192:193], v[84:85], v[76:77]
	s_nop 0
	v_addc_co_u32_e32 v75, vcc, 0, v207, vcc
	v_pk_add_f32 v[80:81], v[198:199], v[80:81]
	v_pk_add_f32 v[78:79], v[200:201], v[78:79]
	v_pk_add_f32 v[88:89], v[188:189], v[76:77]
	s_and_b64 vcc, exec, s[42:43]
	global_store_dwordx4 v[108:109], v[78:81], off nt
	global_store_dwordx4 v[74:75], v[86:89], off offset:16 nt
	s_cbranch_vccnz .LBB0_994
	v_add_co_u32_e32 v82, vcc, 0x18000, v204
	v_cvt_pk_bf16_f32 v74, v78, v79
	v_cvt_pk_bf16_f32 v75, v80, v81
	v_cvt_pk_bf16_f32 v76, v86, v87
	v_cvt_pk_bf16_f32 v77, v88, v89
	s_nop 1
	v_addc_co_u32_e32 v83, vcc, 0, v205, vcc
	global_store_dwordx4 v[82:83], v[74:77], off

; __device__ __forceinline__ unsigned cvt_pk_bf16(float lo, float hi) { unsigned r; asm volatile("v_cvt_pk_bf16_f32 %0, %1, %2" : "=v"(r) : "v"(lo), "v"(hi)); return r; }
; __device__ __forceinline__ void stats_mr(const f32x2 s, float& mu, float& r) { mu = s.x * (1.0f / 1024.0f); const float var = s.y * (1.0f / 1024.0f) - mu * mu; r = __builtin_amdgcn_rsqf(var + 1e-5f); }
;     __device__ __forceinline__ void operator()(const f32x4 (&acc)[2][2][4][2], const Unit& u, int wr, int wc, int fr, int fq) const {
;     ...
;         for (int g = 0; g < 8; ++g) { const int ai = g >> 2, m = g & 3; const int rr = ai * HALF + m * 16, rn = ((g + 1) >> 2) * HALF + ((g + 1) & 3) * 16;
;             f32x2 sv_n = sv_c; if (g + 1 < 8) sv_n = *(const f32x2*)(sp + (size_t)rn * 8 + ls);
;             float mu, r; stats_mr(sv_c, mu, r); float s1 = 0.f, s2 = 0.f;
; #pragma unroll
;             for (int bj = 0; bj < 2; ++bj) { const size_t ro = (size_t)rr * ldc + bj * HALF;
;                 f32x4 q0 = p0, q1 = p1;
;                 if (bj == 0) { q0 = *(const f32x4*)(bp + (ro + HALF) * 4 + l4); q1 = *(const f32x4*)(bp + (ro + HALF) * 4 + l4 + 16); }
;                 else if (g + 1 < 8) { q0 = *(const f32x4*)(bp + (size_t)rn * ldc * 4 + l4); q1 = *(const f32x4*)(bp + (size_t)rn * ldc * 4 + l4 + 16); }
;                 const f32x4 z0 = gv[bj][0] * ((p0 - mu) * r) + acc[ai][bj][m][0] + cv[bj][0], z1 = gv[bj][1] * ((p1 - mu) * r) + acc[ai][bj][m][1] + cv[bj][1];
;                 *(f32x4*)(op + ro * 4 + l4) = z0; *(f32x4*)(op + ro * 4 + l4 + 16) = z1;
;                 s1 += ((z0[0] + z0[1]) + (z0[2] + z0[3])) + ((z1[0] + z1[1]) + (z1[2] + z1[3]));
;                 s2 += ((z0[0] * z0[0] + z0[1] * z0[1]) + (z0[2] * z0[2] + z0[3] * z0[3])) + ((z1[0] * z1[0] + z1[1] * z1[1]) + (z1[2] * z1[2] + z1[3] * z1[3]));
;                 if (zb) { u32x4 w; w.x = cvt_pk_bf16(z0[0], z0[1]); w.y = cvt_pk_bf16(z0[2], z0[3]); w.z = cvt_pk_bf16(z1[0], z1[1]); w.w = cvt_pk_bf16(z1[2], z1[3]); *(u32x4*)(zp + ro * 2 + l2) = w; }
.LBB0_998:
	s_or_b64 exec, exec, s[24:25]
	s_mov_b64 s[4:5], 0x80200
	v_lshl_add_u64 v[66:67], v[206:207], 0, s[4:5]
	s_mov_b32 s4, 0x80000
	s_waitcnt lgkmcnt(1)
	v_add_co_u32_e32 v68, vcc, s4, v206
	global_load_dwordx2 v[90:91], v[212:213], off offset:1152
	s_waitcnt lgkmcnt(0)
	v_addc_co_u32_e32 v69, vcc, 0, v207, vcc
	global_load_dwordx4 v[86:89], v[68:69], off offset:512
	global_load_dwordx4 v[78:81], v[66:67], off offset:16
	v_pk_mul_f32 v[96:97], v[106:107], s[54:55] op_sel_hi:[1,0]
	s_nop 0
	v_fma_f32 v66, -v96, v96, v97
	v_add_f32_e32 v66, 0x3727c5ac, v66
	v_rsq_f32_e32 v94, v66
	s_waitcnt vmcnt(8)
	v_sub_f32_e32 v67, v83, v96
	v_sub_f32_e32 v66, v82, v96
	v_sub_f32_e32 v69, v85, v96
	v_pk_mul_f32 v[66:67], v[94:95], v[66:67] op_sel_hi:[0,1]
	v_sub_f32_e32 v68, v84, v96
	v_pk_fma_f32 v[62:63], v[202:203], v[66:67], v[62:63]
	s_waitcnt vmcnt(7)
	v_sub_f32_e32 v67, v75, v96
	v_sub_f32_e32 v66, v74, v96
	v_pk_mul_f32 v[68:69], v[94:95], v[68:69] op_sel_hi:[0,1]
	v_pk_mul_f32 v[66:67], v[94:95], v[66:67] op_sel_hi:[0,1]
	v_pk_fma_f32 v[64:65], v[196:197], v[68:69], v[64:65]
	v_sub_f32_e32 v69, v77, v96
	v_sub_f32_e32 v68, v76, v96
	v_pk_fma_f32 v[58:59], v[194:195], v[66:67], v[58:59]
	v_pk_mul_f32 v[68:69], v[94:95], v[68:69] op_sel_hi:[0,1]
	v_pk_add_f32 v[70:71], v[190:191], v[58:59]
	v_add_co_u32_e32 v58, vcc, 0x80000, v206
	v_pk_fma_f32 v[60:61], v[192:193], v[68:69], v[60:61]
	s_nop 0
	v_addc_co_u32_e32 v59, vcc, 0, v207, vcc
	v_pk_add_f32 v[64:65], v[198:199], v[64:65]
	v_pk_add_f32 v[62:63], v[200:201], v[62:63]
	v_pk_add_f32 v[72:73], v[188:189], v[60:61]
	s_and_b64 vcc, exec, s[42:43]
	global_store_dwordx4 v[92:93], v[62:65], off nt
	global_store_dwordx4 v[58:59], v[70:73], off offset:16 nt
	s_cbranch_vccnz .LBB0_1000
	v_add_co_u32_e32 v66, vcc, 0x40000, v204
	v_cvt_pk_bf16_f32 v58, v62, v63
	v_cvt_pk_bf16_f32 v59, v64, v65
	v_cvt_pk_bf16_f32 v60, v70, v71
	v_cvt_pk_bf16_f32 v61, v72, v73
	s_nop 1
	v_addc_co_u32_e32 v67, vcc, 0, v205, vcc
	global_store_dwordx4 v[66:67], v[58:61], off

; __device__ __forceinline__ unsigned cvt_pk_bf16(float lo, float hi) { unsigned r; asm volatile("v_cvt_pk_bf16_f32 %0, %1, %2" : "=v"(r) : "v"(lo), "v"(hi)); return r; }
; __device__ __forceinline__ void stats_mr(const f32x2 s, float& mu, float& r) { mu = s.x * (1.0f / 1024.0f); const float var = s.y * (1.0f / 1024.0f) - mu * mu; r = __builtin_amdgcn_rsqf(var + 1e-5f); }
;     __device__ __forceinline__ void operator()(const f32x4 (&acc)[2][2][4][2], const Unit& u, int wr, int wc, int fr, int fq) const {
;     ...
;         for (int g = 0; g < 8; ++g) { const int ai = g >> 2, m = g & 3; const int rr = ai * HALF + m * 16, rn = ((g + 1) >> 2) * HALF + ((g + 1) & 3) * 16;
;             f32x2 sv_n = sv_c; if (g + 1 < 8) sv_n = *(const f32x2*)(sp + (size_t)rn * 8 + ls);
;             float mu, r; stats_mr(sv_c, mu, r); float s1 = 0.f, s2 = 0.f;
; #pragma unroll
;             for (int bj = 0; bj < 2; ++bj) { const size_t ro = (size_t)rr * ldc + bj * HALF;
;                 f32x4 q0 = p0, q1 = p1;
;                 if (bj == 0) { q0 = *(const f32x4*)(bp + (ro + HALF) * 4 + l4); q1 = *(const f32x4*)(bp + (ro + HALF) * 4 + l4 + 16); }
;                 else if (g + 1 < 8) { q0 = *(const f32x4*)(bp + (size_t)rn * ldc * 4 + l4); q1 = *(const f32x4*)(bp + (size_t)rn * ldc * 4 + l4 + 16); }
;                 const f32x4 z0 = gv[bj][0] * ((p0 - mu) * r) + acc[ai][bj][m][0] + cv[bj][0], z1 = gv[bj][1] * ((p1 - mu) * r) + acc[ai][bj][m][1] + cv[bj][1];
;                 *(f32x4*)(op + ro * 4 + l4) = z0; *(f32x4*)(op + ro * 4 + l4 + 16) = z1;
;                 s1 += ((z0[0] + z0[1]) + (z0[2] + z0[3])) + ((z1[0] + z1[1]) + (z1[2] + z1[3]));
;                 s2 += ((z0[0] * z0[0] + z0[1] * z0[1]) + (z0[2] * z0[2] + z0[3] * z0[3])) + ((z1[0] * z1[0] + z1[1] * z1[1]) + (z1[2] * z1[2] + z1[3] * z1[3]));
;                 if (zb) { u32x4 w; w.x = cvt_pk_bf16(z0[0], z0[1]); w.y = cvt_pk_bf16(z0[2], z0[3]); w.z = cvt_pk_bf16(z1[0], z1[1]); w.w = cvt_pk_bf16(z1[2], z1[3]); *(u32x4*)(zp + ro * 2 + l2) = w; }
.LBB0_1004:
	s_or_b64 exec, exec, s[24:25]
	s_waitcnt lgkmcnt(1)
	v_add_co_u32_e32 v52, vcc, s79, v206
	s_mov_b64 s[4:5], 0x90200
	s_waitcnt lgkmcnt(0)
	v_addc_co_u32_e32 v53, vcc, 0, v207, vcc
	global_load_dwordx2 v[74:75], v[212:213], off offset:1280
	v_lshl_add_u64 v[50:51], v[206:207], 0, s[4:5]
	global_load_dwordx4 v[70:73], v[52:53], off offset:512
	global_load_dwordx4 v[62:65], v[50:51], off offset:16
	v_pk_mul_f32 v[80:81], v[90:91], s[54:55] op_sel_hi:[1,0]
	s_nop 0
	v_fma_f32 v50, -v80, v80, v81
	v_add_f32_e32 v50, 0x3727c5ac, v50
	v_rsq_f32_e32 v78, v50
	s_waitcnt vmcnt(8)
	v_sub_f32_e32 v51, v67, v80
	v_sub_f32_e32 v50, v66, v80
	v_sub_f32_e32 v53, v69, v80
	v_pk_mul_f32 v[50:51], v[78:79], v[50:51] op_sel_hi:[0,1]
	v_sub_f32_e32 v52, v68, v80
	v_pk_fma_f32 v[46:47], v[202:203], v[50:51], v[46:47]
	s_waitcnt vmcnt(7)
	v_sub_f32_e32 v51, v59, v80
	v_sub_f32_e32 v50, v58, v80
	v_pk_mul_f32 v[52:53], v[78:79], v[52:53] op_sel_hi:[0,1]
	v_pk_mul_f32 v[50:51], v[78:79], v[50:51] op_sel_hi:[0,1]
	v_pk_fma_f32 v[48:49], v[196:197], v[52:53], v[48:49]
	v_sub_f32_e32 v53, v61, v80
	v_sub_f32_e32 v52, v60, v80
	v_pk_fma_f32 v[42:43], v[194:195], v[50:51], v[42:43]
	v_pk_mul_f32 v[52:53], v[78:79], v[52:53] op_sel_hi:[0,1]
	v_pk_add_f32 v[54:55], v[190:191], v[42:43]
	v_add_co_u32_e32 v42, vcc, 0x90000, v206
	v_pk_fma_f32 v[44:45], v[192:193], v[52:53], v[44:45]
	s_nop 0
	v_addc_co_u32_e32 v43, vcc, 0, v207, vcc
	v_pk_add_f32 v[48:49], v[198:199], v[48:49]
	v_pk_add_f32 v[46:47], v[200:201], v[46:47]
	v_pk_add_f32 v[56:57], v[188:189], v[44:45]
	s_and_b64 vcc, exec, s[42:43]
	global_store_dwordx4 v[76:77], v[46:49], off nt
	global_store_dwordx4 v[42:43], v[54:57], off offset:16 nt
	s_cbranch_vccnz .LBB0_1006
	v_add_co_u32_e32 v50, vcc, 0x48000, v204
	v_cvt_pk_bf16_f32 v42, v46, v47
	v_cvt_pk_bf16_f32 v43, v48, v49
	v_cvt_pk_bf16_f32 v44, v54, v55
	v_cvt_pk_bf16_f32 v45, v56, v57
	s_nop 1
	v_addc_co_u32_e32 v51, vcc, 0, v205, vcc
	global_store_dwordx4 v[50:51], v[42:45], off

; __device__ __forceinline__ unsigned cvt_pk_bf16(float lo, float hi) { unsigned r; asm volatile("v_cvt_pk_bf16_f32 %0, %1, %2" : "=v"(r) : "v"(lo), "v"(hi)); return r; }
; __device__ __forceinline__ void stats_mr(const f32x2 s, float& mu, float& r) { mu = s.x * (1.0f / 1024.0f); const float var = s.y * (1.0f / 1024.0f) - mu * mu; r = __builtin_amdgcn_rsqf(var + 1e-5f); }
;     __device__ __forceinline__ void operator()(const f32x4 (&acc)[2][2][4][2], const Unit& u, int wr, int wc, int fr, int fq) const {
;     ...
;         for (int g = 0; g < 8; ++g) { const int ai = g >> 2, m = g & 3; const int rr = ai * HALF + m * 16, rn = ((g + 1) >> 2) * HALF + ((g + 1) & 3) * 16;
;             f32x2 sv_n = sv_c; if (g + 1 < 8) sv_n = *(const f32x2*)(sp + (size_t)rn * 8 + ls);
;             float mu, r; stats_mr(sv_c, mu, r); float s1 = 0.f, s2 = 0.f;
; #pragma unroll
;             for (int bj = 0; bj < 2; ++bj) { const size_t ro = (size_t)rr * ldc + bj * HALF;
;                 f32x4 q0 = p0, q1 = p1;
;                 if (bj == 0) { q0 = *(const f32x4*)(bp + (ro + HALF) * 4 + l4); q1 = *(const f32x4*)(bp + (ro + HALF) * 4 + l4 + 16); }
;                 else if (g + 1 < 8) { q0 = *(const f32x4*)(bp + (size_t)rn * ldc * 4 + l4); q1 = *(const f32x4*)(bp + (size_t)rn * ldc * 4 + l4 + 16); }
;                 const f32x4 z0 = gv[bj][0] * ((p0 - mu) * r) + acc[ai][bj][m][0] + cv[bj][0], z1 = gv[bj][1] * ((p1 - mu) * r) + acc[ai][bj][m][1] + cv[bj][1];
;                 *(f32x4*)(op + ro * 4 + l4) = z0; *(f32x4*)(op + ro * 4 + l4 + 16) = z1;
;                 s1 += ((z0[0] + z0[1]) + (z0[2] + z0[3])) + ((z1[0] + z1[1]) + (z1[2] + z1[3]));
;                 s2 += ((z0[0] * z0[0] + z0[1] * z0[1]) + (z0[2] * z0[2] + z0[3] * z0[3])) + ((z1[0] * z1[0] + z1[1] * z1[1]) + (z1[2] * z1[2] + z1[3] * z1[3]));
;                 if (zb) { u32x4 w; w.x = cvt_pk_bf16(z0[0], z0[1]); w.y = cvt_pk_bf16(z0[2], z0[3]); w.z = cvt_pk_bf16(z1[0], z1[1]); w.w = cvt_pk_bf16(z1[2], z1[3]); *(u32x4*)(zp + ro * 2 + l2) = w; }
.LBB0_1010:
	s_or_b64 exec, exec, s[24:25]
	s_mov_b64 s[4:5], 0xa0200
	v_lshl_add_u64 v[34:35], v[206:207], 0, s[4:5]
	s_mov_b32 s4, 0xa0000
	s_waitcnt lgkmcnt(1)
	v_add_co_u32_e32 v36, vcc, s4, v206
	global_load_dwordx2 v[58:59], v[212:213], off offset:1408
	s_waitcnt lgkmcnt(0)
	v_addc_co_u32_e32 v37, vcc, 0, v207, vcc
	global_load_dwordx4 v[54:57], v[36:37], off offset:512
	global_load_dwordx4 v[46:49], v[34:35], off offset:16
	v_pk_mul_f32 v[64:65], v[74:75], s[54:55] op_sel_hi:[1,0]
	s_nop 0
	v_fma_f32 v34, -v64, v64, v65
	v_add_f32_e32 v34, 0x3727c5ac, v34
	v_rsq_f32_e32 v62, v34
	s_waitcnt vmcnt(8)
	v_sub_f32_e32 v35, v51, v64
	v_sub_f32_e32 v34, v50, v64
	v_sub_f32_e32 v37, v53, v64
	v_pk_mul_f32 v[34:35], v[62:63], v[34:35] op_sel_hi:[0,1]
	v_sub_f32_e32 v36, v52, v64
	v_pk_fma_f32 v[30:31], v[202:203], v[34:35], v[30:31]
	s_waitcnt vmcnt(7)
	v_sub_f32_e32 v35, v43, v64
	v_sub_f32_e32 v34, v42, v64
	v_pk_mul_f32 v[36:37], v[62:63], v[36:37] op_sel_hi:[0,1]
	v_pk_mul_f32 v[34:35], v[62:63], v[34:35] op_sel_hi:[0,1]
	v_pk_fma_f32 v[32:33], v[196:197], v[36:37], v[32:33]
	v_sub_f32_e32 v37, v45, v64
	v_sub_f32_e32 v36, v44, v64
	v_pk_fma_f32 v[26:27], v[194:195], v[34:35], v[26:27]
	v_pk_mul_f32 v[36:37], v[62:63], v[36:37] op_sel_hi:[0,1]
	v_pk_add_f32 v[38:39], v[190:191], v[26:27]
	v_add_co_u32_e32 v26, vcc, 0xa0000, v206
	v_pk_fma_f32 v[28:29], v[192:193], v[36:37], v[28:29]
	s_nop 0
	v_addc_co_u32_e32 v27, vcc, 0, v207, vcc
	v_pk_add_f32 v[32:33], v[198:199], v[32:33]
	v_pk_add_f32 v[30:31], v[200:201], v[30:31]
	v_pk_add_f32 v[40:41], v[188:189], v[28:29]
	s_and_b64 vcc, exec, s[42:43]
	global_store_dwordx4 v[60:61], v[30:33], off nt
	global_store_dwordx4 v[26:27], v[38:41], off offset:16 nt
	s_cbranch_vccnz .LBB0_1012
	v_add_co_u32_e32 v34, vcc, 0x50000, v204
	v_cvt_pk_bf16_f32 v26, v30, v31
	v_cvt_pk_bf16_f32 v27, v32, v33
	v_cvt_pk_bf16_f32 v28, v38, v39
	v_cvt_pk_bf16_f32 v29, v40, v41
	s_nop 1
	v_addc_co_u32_e32 v35, vcc, 0, v205, vcc
	global_store_dwordx4 v[34:35], v[26:29], off

; __device__ __forceinline__ unsigned cvt_pk_bf16(float lo, float hi) { unsigned r; asm volatile("v_cvt_pk_bf16_f32 %0, %1, %2" : "=v"(r) : "v"(lo), "v"(hi)); return r; }
; __device__ __forceinline__ void stats_mr(const f32x2 s, float& mu, float& r) { mu = s.x * (1.0f / 1024.0f); const float var = s.y * (1.0f / 1024.0f) - mu * mu; r = __builtin_amdgcn_rsqf(var + 1e-5f); }
;     __device__ __forceinline__ void operator()(const f32x4 (&acc)[2][2][4][2], const Unit& u, int wr, int wc, int fr, int fq) const {
;     ...
;         for (int g = 0; g < 8; ++g) { const int ai = g >> 2, m = g & 3; const int rr = ai * HALF + m * 16, rn = ((g + 1) >> 2) * HALF + ((g + 1) & 3) * 16;
;             f32x2 sv_n = sv_c; if (g + 1 < 8) sv_n = *(const f32x2*)(sp + (size_t)rn * 8 + ls);
;             float mu, r; stats_mr(sv_c, mu, r); float s1 = 0.f, s2 = 0.f;
; #pragma unroll
;             for (int bj = 0; bj < 2; ++bj) { const size_t ro = (size_t)rr * ldc + bj * HALF;
;                 f32x4 q0 = p0, q1 = p1;
;                 if (bj == 0) { q0 = *(const f32x4*)(bp + (ro + HALF) * 4 + l4); q1 = *(const f32x4*)(bp + (ro + HALF) * 4 + l4 + 16); }
;                 else if (g + 1 < 8) { q0 = *(const f32x4*)(bp + (size_t)rn * ldc * 4 + l4); q1 = *(const f32x4*)(bp + (size_t)rn * ldc * 4 + l4 + 16); }
;                 const f32x4 z0 = gv[bj][0] * ((p0 - mu) * r) + acc[ai][bj][m][0] + cv[bj][0], z1 = gv[bj][1] * ((p1 - mu) * r) + acc[ai][bj][m][1] + cv[bj][1];
;                 *(f32x4*)(op + ro * 4 + l4) = z0; *(f32x4*)(op + ro * 4 + l4 + 16) = z1;
;                 s1 += ((z0[0] + z0[1]) + (z0[2] + z0[3])) + ((z1[0] + z1[1]) + (z1[2] + z1[3]));
;                 s2 += ((z0[0] * z0[0] + z0[1] * z0[1]) + (z0[2] * z0[2] + z0[3] * z0[3])) + ((z1[0] * z1[0] + z1[1] * z1[1]) + (z1[2] * z1[2] + z1[3] * z1[3]));
;                 if (zb) { u32x4 w; w.x = cvt_pk_bf16(z0[0], z0[1]); w.y = cvt_pk_bf16(z0[2], z0[3]); w.z = cvt_pk_bf16(z1[0], z1[1]); w.w = cvt_pk_bf16(z1[2], z1[3]); *(u32x4*)(zp + ro * 2 + l2) = w; }
.LBB0_1016:
	s_or_b64 exec, exec, s[24:25]
	s_mov_b64 s[4:5], 0xb0200
	v_lshl_add_u64 v[18:19], v[206:207], 0, s[4:5]
	s_mov_b32 s4, 0xb0000
	s_waitcnt lgkmcnt(1)
	v_add_co_u32_e32 v20, vcc, s4, v206
	v_pk_mul_f32 v[32:33], v[58:59], s[54:55] op_sel_hi:[1,0]
	s_waitcnt lgkmcnt(0)
	v_addc_co_u32_e32 v21, vcc, 0, v207, vcc
	global_load_dwordx4 v[22:25], v[20:21], off offset:512
	s_nop 0
	global_load_dwordx4 v[18:21], v[18:19], off offset:16
	v_fma_f32 v30, -v32, v32, v33
	v_add_f32_e32 v30, 0x3727c5ac, v30
	v_rsq_f32_e32 v30, v30
	s_waitcnt vmcnt(6)
	v_sub_f32_e32 v27, v27, v32
	v_sub_f32_e32 v26, v26, v32
	v_sub_f32_e32 v35, v35, v32
	v_sub_f32_e32 v34, v34, v32
	v_sub_f32_e32 v37, v37, v32
	v_sub_f32_e32 v36, v36, v32
	v_sub_f32_e32 v29, v29, v32
	v_sub_f32_e32 v28, v28, v32
	v_pk_mul_f32 v[26:27], v[30:31], v[26:27] op_sel_hi:[0,1]
	v_pk_mul_f32 v[36:37], v[30:31], v[36:37] op_sel_hi:[0,1]
	v_pk_mul_f32 v[34:35], v[30:31], v[34:35] op_sel_hi:[0,1]
	v_pk_mul_f32 v[28:29], v[30:31], v[28:29] op_sel_hi:[0,1]
	v_pk_fma_f32 v[10:11], v[194:195], v[26:27], v[10:11]
	v_add_co_u32_e32 v26, vcc, 0xb0000, v206
	v_pk_fma_f32 v[14:15], v[202:203], v[34:35], v[14:15]
	v_pk_fma_f32 v[16:17], v[196:197], v[36:37], v[16:17]
	v_pk_fma_f32 v[12:13], v[192:193], v[28:29], v[12:13]
	v_addc_co_u32_e32 v27, vcc, 0, v207, vcc
	v_pk_add_f32 v[16:17], v[198:199], v[16:17]
	v_pk_add_f32 v[14:15], v[200:201], v[14:15]
	v_pk_add_f32 v[12:13], v[188:189], v[12:13]
	v_pk_add_f32 v[10:11], v[190:191], v[10:11]
	s_and_b64 vcc, exec, s[42:43]
	global_store_dwordx4 v[42:43], v[14:17], off nt
	global_store_dwordx4 v[26:27], v[10:13], off offset:16 nt
	s_cbranch_vccnz .LBB0_1018
	v_add_co_u32_e32 v34, vcc, 0x58000, v204
	v_cvt_pk_bf16_f32 v26, v14, v15
	v_cvt_pk_bf16_f32 v27, v16, v17
	v_cvt_pk_bf16_f32 v28, v10, v11
	v_cvt_pk_bf16_f32 v29, v12, v13
	s_nop 1
	v_addc_co_u32_e32 v35, vcc, 0, v205, vcc
	global_store_dwordx4 v[34:35], v[26:29], off
